# v27: v26 plus m0 setup of each tile DMA hoisted before the gap's fragment reads (no s_nop pads)
# baseline (speedup 1.0000x reference)
; #define SBAR() __builtin_amdgcn_sched_barrier(0)
; #define PVR(S, DA, DB, vbase) do { S[0] = tr_read<v_rd_off(DA, 0, 0)>(vbase); S[1] = tr_read<v_rd_off(DA, 0, 1)>(vbase); S[2] = tr_read<v_rd_off(DB, 0, 0)>(vbase); S[3] = tr_read<v_rd_off(DB, 0, 1)>(vbase); \
;     S[4] = tr_read<v_rd_off(DA, 1, 0)>(vbase); S[5] = tr_read<v_rd_off(DA, 1, 1)>(vbase); S[6] = tr_read<v_rd_off(DB, 1, 0)>(vbase); S[7] = tr_read<v_rd_off(DB, 1, 1)>(vbase); } while (0)
; #define RAWBAR() do { asm volatile("s_waitcnt lgkmcnt(0)" ::: "memory"); __builtin_amdgcn_s_barrier(); asm volatile("" ::: "memory"); } while (0)
; #define RAWBAR() do { asm volatile("s_waitcnt lgkmcnt(0)" ::: "memory"); __builtin_amdgcn_s_barrier(); asm volatile("" ::: "memory"); } while (0)
; #define RAWBAR() do { asm volatile("s_waitcnt lgkmcnt(0)" ::: "memory"); __builtin_amdgcn_s_barrier(); asm volatile("" ::: "memory"); } while (0)
; #define RAWBAR() do { asm volatile("s_waitcnt lgkmcnt(0)" ::: "memory"); __builtin_amdgcn_s_barrier(); asm volatile("" ::: "memory"); } while (0)
; #define RAWBAR() do { asm volatile("s_waitcnt lgkmcnt(0)" ::: "memory"); __builtin_amdgcn_s_barrier(); asm volatile("" ::: "memory"); } while (0)
; template <int MODE> ...
;     ...
;   for (int j = 0; j < NT; ++j) {
;     const int buf = j & 1;
;     if (j + 1 < NT) { STAGE((j + 1) * KVBLK, buf ^ 1); }
;     const char* Kb = K_lds + buf * 16384;
;     f32x16 pe = {}, po = {};
; #pragma unroll
;     for (int d0 = 0; d0 < 8; d0 += 2) {
;       const bf16x8 k0 = *reinterpret_cast<const bf16x8*>(Kb + KSWZ(krow, (d0 * 16 + hi * 8) * 2));
;       const bf16x8 k1 = *reinterpret_cast<const bf16x8*>(Kb + KSWZ(krow, ((d0 + 1) * 16 + hi * 8) * 2));
;       pe = __builtin_amdgcn_mfma_f32_32x32x16_bf16(k0, qr[d0], pe, 0, 0, 0);
;       po = __builtin_amdgcn_mfma_f32_32x32x16_bf16(k1, qr[d0 + 1], po, 0, 0, 0); }
;     const int vo = vb0 + buf * 32768;
;     s16x4 R0_[8], R1_[8];
;     PVR(R0_, 0, 1, vo);
;     f32x16 p;
; #pragma unroll
;     for (int r = 0; r < 16; ++r) p[r] = __builtin_amdgcn_exp2f(fmaf(pe[r] + po[r], C, negMc));
;     float ps = 0.f;
; #pragma unroll
;     for (int r = 0; r < 16; ++r) ps += p[r];
;     lsum += ps;
;     const bf16x8 own0 = pk8(p, 0), own1 = pk8(p, 8);
;     SBAR();
;     PV_TAIL4(o, vo, vo + 16384, own0, own1);
;     asm volatile("s_waitcnt vmcnt(0)" ::: "memory");
;     RAWBAR();
;   }
.LBB0_1019:
	ds_read_b128 v[226:229], v225 offset:16384
	ds_read_b128 v[230:233], v223 offset:16384
	ds_read_b128 v[234:237], v222 offset:16384
	ds_read_b128 v[238:241], v221 offset:16384
	v_exp_f32_e32 v144, v144
	v_exp_f32_e32 v145, v145
	v_exp_f32_e32 v146, v146
	v_exp_f32_e32 v147, v147
	s_waitcnt lgkmcnt(2)
	v_mfma_f32_32x32x16_bf16 v[128:143], v[226:229], v[188:191], 0
	v_mfma_f32_32x32x16_bf16 v[128:143], v[230:233], v[184:187], v[128:143]
	ds_read_b128 v[226:229], v202 offset:16384
	ds_read_b128 v[230:233], v203 offset:16384
	s_mov_b32 m0, s24
	s_nop 0
	global_load_lds_dwordx4 v220, s[86:87] sc1
	v_exp_f32_e32 v148, v148
	v_exp_f32_e32 v149, v149
	v_exp_f32_e32 v150, v150
	v_exp_f32_e32 v151, v151
	v_add_f32_e32 v246, v144, v145
	v_add_f32_e32 v246, v146, v246
	v_add_f32_e32 v246, v147, v246
	s_waitcnt lgkmcnt(2)
	v_mfma_f32_32x32x16_bf16 v[128:143], v[234:237], v[180:183], v[128:143]
	v_mfma_f32_32x32x16_bf16 v[128:143], v[238:241], v[176:179], v[128:143]
	ds_read_b128 v[234:237], v204 offset:16384
	ds_read_b128 v[238:241], v205 offset:16384
	s_add_i32 m0, s24, 0x2000
	s_nop 0
	global_load_lds_dwordx4 v219, s[86:87] sc1
	v_exp_f32_e32 v152, v152
	v_exp_f32_e32 v153, v153
	v_exp_f32_e32 v154, v154
	v_exp_f32_e32 v155, v155
	v_add_f32_e32 v246, v148, v246
	v_add_f32_e32 v246, v149, v246
	v_add_f32_e32 v246, v150, v246
	v_add_f32_e32 v246, v151, v246
	s_waitcnt lgkmcnt(2)
	v_mfma_f32_32x32x16_bf16 v[128:143], v[226:229], v[172:175], v[128:143]
	v_mfma_f32_32x32x16_bf16 v[128:143], v[230:233], v[168:171], v[128:143]
	v_exp_f32_e32 v156, v156
	v_exp_f32_e32 v157, v157
	v_exp_f32_e32 v158, v158
	v_exp_f32_e32 v159, v159
	v_add_f32_e32 v246, v152, v246
	v_add_f32_e32 v246, v153, v246
	v_add_f32_e32 v246, v154, v246
	v_add_f32_e32 v246, v155, v246
	v_cvt_pk_bf16_f32 v226, v144, v145
	v_cvt_pk_bf16_f32 v227, v146, v147
	v_cvt_pk_bf16_f32 v228, v148, v149
	v_cvt_pk_bf16_f32 v229, v150, v151
	s_waitcnt lgkmcnt(0)
	v_mfma_f32_32x32x16_bf16 v[128:143], v[234:237], v[164:167], v[128:143]
	v_mfma_f32_32x32x16_bf16 v[128:143], v[238:241], v[160:163], v[128:143]
	v_add_u32_e32 v245, s84, v214
	s_add_i32 s85, s84, 0x8000
	s_cmp_eq_u32 s85, 0x18000
	s_cselect_b32 s85, 0, s85
	ds_read_b64_tr_b16 v[234:235], v245 offset:0
	ds_read_b64_tr_b16 v[236:237], v245 offset:2048
	ds_read_b64_tr_b16 v[238:239], v245 offset:512
	ds_read_b64_tr_b16 v[240:241], v245 offset:2560
	ds_read_b64_tr_b16 v[144:145], v245 offset:4096
	ds_read_b64_tr_b16 v[146:147], v245 offset:6144
	ds_read_b64_tr_b16 v[148:149], v245 offset:4608
	ds_read_b64_tr_b16 v[150:151], v245 offset:6656
	v_add_f32_e32 v246, v156, v246
	v_add_f32_e32 v246, v157, v246
	v_add_f32_e32 v246, v158, v246
	v_add_f32_e32 v246, v159, v246
	v_cvt_pk_bf16_f32 v230, v152, v153
	v_cvt_pk_bf16_f32 v231, v154, v155
	v_cvt_pk_bf16_f32 v232, v156, v157
	v_cvt_pk_bf16_f32 v233, v158, v159
	v_add_f32_e32 v215, v215, v246
	ds_read_b64_tr_b16 v[152:153], v245 offset:1024
	ds_read_b64_tr_b16 v[154:155], v245 offset:3072
	ds_read_b64_tr_b16 v[156:157], v245 offset:1536
	ds_read_b64_tr_b16 v[158:159], v245 offset:3584
	s_waitcnt lgkmcnt(8)
	v_mfma_f32_32x32x16_bf16 v[112:127], v[226:229], v[234:237], v[112:127]
	v_mfma_f32_32x32x16_bf16 v[96:111], v[226:229], v[238:241], v[96:111]
	s_add_i32 s41, s85, s24
	s_add_i32 m0, s41, 0x8000
	ds_read_b64_tr_b16 v[234:235], v245 offset:5120
	ds_read_b64_tr_b16 v[236:237], v245 offset:7168
	ds_read_b64_tr_b16 v[238:239], v245 offset:5632
	ds_read_b64_tr_b16 v[240:241], v245 offset:7680
	global_load_lds_dwordx4 v218, s[2:3] sc1
	s_waitcnt lgkmcnt(8)
	v_mfma_f32_32x32x16_bf16 v[112:127], v[230:233], v[144:147], v[112:127]
	v_mfma_f32_32x32x16_bf16 v[96:111], v[230:233], v[148:151], v[96:111]
	s_add_i32 s41, s85, s24
	s_add_i32 m0, s41, 0xa000
	ds_read_b64_tr_b16 v[144:145], v245 offset:16384
	ds_read_b64_tr_b16 v[146:147], v245 offset:18432
	ds_read_b64_tr_b16 v[148:149], v245 offset:16896
	ds_read_b64_tr_b16 v[150:151], v245 offset:18944
	global_load_lds_dwordx4 v217, s[2:3] sc1
	s_waitcnt lgkmcnt(8)
	v_mfma_f32_32x32x16_bf16 v[80:95], v[226:229], v[152:155], v[80:95]
	v_mfma_f32_32x32x16_bf16 v[64:79], v[226:229], v[156:159], v[64:79]
	s_add_i32 s41, s85, s24
	s_add_i32 m0, s41, 0xc000
	ds_read_b64_tr_b16 v[152:153], v245 offset:20480
	ds_read_b64_tr_b16 v[154:155], v245 offset:22528
	ds_read_b64_tr_b16 v[156:157], v245 offset:20992
	ds_read_b64_tr_b16 v[158:159], v245 offset:23040
	global_load_lds_dwordx4 v242, s[2:3] sc1
	s_waitcnt lgkmcnt(8)
	v_mfma_f32_32x32x16_bf16 v[80:95], v[230:233], v[234:237], v[80:95]
	v_mfma_f32_32x32x16_bf16 v[64:79], v[230:233], v[238:241], v[64:79]
	s_add_i32 s41, s85, s24
	s_add_i32 m0, s41, 0xe000
	ds_read_b64_tr_b16 v[234:235], v245 offset:17408
	ds_read_b64_tr_b16 v[236:237], v245 offset:19456
	ds_read_b64_tr_b16 v[238:239], v245 offset:17920
	ds_read_b64_tr_b16 v[240:241], v245 offset:19968
	global_load_lds_dwordx4 v243, s[2:3] sc1
	s_waitcnt lgkmcnt(8)
	v_mfma_f32_32x32x16_bf16 v[48:63], v[226:229], v[144:147], v[48:63]
	v_mfma_f32_32x32x16_bf16 v[32:47], v[226:229], v[148:151], v[32:47]
	ds_read_b64_tr_b16 v[144:145], v245 offset:21504
	ds_read_b64_tr_b16 v[146:147], v245 offset:23552
	ds_read_b64_tr_b16 v[148:149], v245 offset:22016
	ds_read_b64_tr_b16 v[150:151], v245 offset:24064
	s_waitcnt lgkmcnt(8)
	v_mfma_f32_32x32x16_bf16 v[48:63], v[230:233], v[152:155], v[48:63]
	v_mfma_f32_32x32x16_bf16 v[32:47], v[230:233], v[156:159], v[32:47]
	s_waitcnt lgkmcnt(0)
	v_mfma_f32_32x32x16_bf16 v[16:31], v[226:229], v[234:237], v[16:31]
	s_waitcnt vmcnt(0)
	s_barrier
; #define SBAR() __builtin_amdgcn_sched_barrier(0)
; #define PVR(S, DA, DB, vbase) do { S[0] = tr_read<v_rd_off(DA, 0, 0)>(vbase); S[1] = tr_read<v_rd_off(DA, 0, 1)>(vbase); S[2] = tr_read<v_rd_off(DB, 0, 0)>(vbase); S[3] = tr_read<v_rd_off(DB, 0, 1)>(vbase); \
;     S[4] = tr_read<v_rd_off(DA, 1, 0)>(vbase); S[5] = tr_read<v_rd_off(DA, 1, 1)>(vbase); S[6] = tr_read<v_rd_off(DB, 1, 0)>(vbase); S[7] = tr_read<v_rd_off(DB, 1, 1)>(vbase); } while (0)
; #define RAWBAR() do { asm volatile("s_waitcnt lgkmcnt(0)" ::: "memory"); __builtin_amdgcn_s_barrier(); asm volatile("" ::: "memory"); } while (0)
; #define RAWBAR() do { asm volatile("s_waitcnt lgkmcnt(0)" ::: "memory"); __builtin_amdgcn_s_barrier(); asm volatile("" ::: "memory"); } while (0)
; #define RAWBAR() do { asm volatile("s_waitcnt lgkmcnt(0)" ::: "memory"); __builtin_amdgcn_s_barrier(); asm volatile("" ::: "memory"); } while (0)
; #define RAWBAR() do { asm volatile("s_waitcnt lgkmcnt(0)" ::: "memory"); __builtin_amdgcn_s_barrier(); asm volatile("" ::: "memory"); } while (0)
; #define RAWBAR() do { asm volatile("s_waitcnt lgkmcnt(0)" ::: "memory"); __builtin_amdgcn_s_barrier(); asm volatile("" ::: "memory"); } while (0)
; template <int MODE> ...
;     ...
;   for (int j = 0; j < NT; ++j) {
;     const int buf = j & 1;
;     if (j + 1 < NT) { STAGE((j + 1) * KVBLK, buf ^ 1); }
;     const char* Kb = K_lds + buf * 16384;
;     f32x16 pe = {}, po = {};
; #pragma unroll
;     for (int d0 = 0; d0 < 8; d0 += 2) {
;       const bf16x8 k0 = *reinterpret_cast<const bf16x8*>(Kb + KSWZ(krow, (d0 * 16 + hi * 8) * 2));
;       const bf16x8 k1 = *reinterpret_cast<const bf16x8*>(Kb + KSWZ(krow, ((d0 + 1) * 16 + hi * 8) * 2));
;       pe = __builtin_amdgcn_mfma_f32_32x32x16_bf16(k0, qr[d0], pe, 0, 0, 0);
;       po = __builtin_amdgcn_mfma_f32_32x32x16_bf16(k1, qr[d0 + 1], po, 0, 0, 0); }
;     const int vo = vb0 + buf * 32768;
;     s16x4 R0_[8], R1_[8];
;     PVR(R0_, 0, 1, vo);
;     f32x16 p;
; #pragma unroll
;     for (int r = 0; r < 16; ++r) p[r] = __builtin_amdgcn_exp2f(fmaf(pe[r] + po[r], C, negMc));
;     float ps = 0.f;
; #pragma unroll
;     for (int r = 0; r < 16; ++r) ps += p[r];
;     lsum += ps;
;     const bf16x8 own0 = pk8(p, 0), own1 = pk8(p, 8);
;     SBAR();
;     PV_TAIL4(o, vo, vo + 16384, own0, own1);
;     asm volatile("s_waitcnt vmcnt(0)" ::: "memory");
;     RAWBAR();
;   }
	s_add_u32 s86, s86, 0x4000
	s_addc_u32 s87, s87, 0
	s_add_u32 s2, s2, 0x8000
	s_addc_u32 s3, s3, 0
	v_mfma_f32_32x32x16_bf16 v[0:15], v[226:229], v[238:241], v[0:15]
	v_mfma_f32_32x32x16_bf16 v[16:31], v[230:233], v[144:147], v[16:31]
	s_add_i32 s84, s84, 0x8000
	s_cmp_eq_u32 s84, 0x18000
	s_cselect_b32 s84, 0, s84
	v_mfma_f32_32x32x16_bf16 v[0:15], v[230:233], v[148:151], v[0:15]
	ds_read_b128 v[226:229], v225 offset:0
	ds_read_b128 v[230:233], v223 offset:0
	ds_read_b128 v[234:237], v222 offset:0
	ds_read_b128 v[238:241], v221 offset:0
	v_exp_f32_e32 v128, v128
	v_exp_f32_e32 v129, v129
	v_exp_f32_e32 v130, v130
	v_exp_f32_e32 v131, v131
	s_waitcnt lgkmcnt(2)
	v_mfma_f32_32x32x16_bf16 v[144:159], v[226:229], v[188:191], 0
	v_mfma_f32_32x32x16_bf16 v[144:159], v[230:233], v[184:187], v[144:159]
	ds_read_b128 v[226:229], v202 offset:0
	ds_read_b128 v[230:233], v203 offset:0
	s_add_i32 m0, s24, 0x4000
	s_nop 0
	global_load_lds_dwordx4 v220, s[86:87] sc1
	v_exp_f32_e32 v132, v132
	v_exp_f32_e32 v133, v133
	v_exp_f32_e32 v134, v134
	v_exp_f32_e32 v135, v135
	v_add_f32_e32 v246, v128, v129
	v_add_f32_e32 v246, v130, v246
	v_add_f32_e32 v246, v131, v246
	s_waitcnt lgkmcnt(2)
	v_mfma_f32_32x32x16_bf16 v[144:159], v[234:237], v[180:183], v[144:159]
	v_mfma_f32_32x32x16_bf16 v[144:159], v[238:241], v[176:179], v[144:159]
	ds_read_b128 v[234:237], v204 offset:0
	ds_read_b128 v[238:241], v205 offset:0
	s_add_i32 m0, s24, 0x6000
	s_nop 0
	global_load_lds_dwordx4 v219, s[86:87] sc1
	v_exp_f32_e32 v136, v136
	v_exp_f32_e32 v137, v137
	v_exp_f32_e32 v138, v138
	v_exp_f32_e32 v139, v139
	v_add_f32_e32 v246, v132, v246
	v_add_f32_e32 v246, v133, v246
	v_add_f32_e32 v246, v134, v246
	v_add_f32_e32 v246, v135, v246
	s_waitcnt lgkmcnt(2)
	v_mfma_f32_32x32x16_bf16 v[144:159], v[226:229], v[172:175], v[144:159]
	v_mfma_f32_32x32x16_bf16 v[144:159], v[230:233], v[168:171], v[144:159]
	v_exp_f32_e32 v140, v140
	v_exp_f32_e32 v141, v141
	v_exp_f32_e32 v142, v142
	v_exp_f32_e32 v143, v143
	v_add_f32_e32 v246, v136, v246
	v_add_f32_e32 v246, v137, v246
	v_add_f32_e32 v246, v138, v246
	v_add_f32_e32 v246, v139, v246
	v_cvt_pk_bf16_f32 v226, v128, v129
	v_cvt_pk_bf16_f32 v227, v130, v131
	v_cvt_pk_bf16_f32 v228, v132, v133
	v_cvt_pk_bf16_f32 v229, v134, v135
	s_waitcnt lgkmcnt(0)
	v_mfma_f32_32x32x16_bf16 v[144:159], v[234:237], v[164:167], v[144:159]
	v_mfma_f32_32x32x16_bf16 v[144:159], v[238:241], v[160:163], v[144:159]
	v_add_u32_e32 v245, s84, v214
	s_add_i32 s85, s84, 0x8000
	s_cmp_eq_u32 s85, 0x18000
	s_cselect_b32 s85, 0, s85
	ds_read_b64_tr_b16 v[234:235], v245 offset:0
	ds_read_b64_tr_b16 v[236:237], v245 offset:2048
	ds_read_b64_tr_b16 v[238:239], v245 offset:512
	ds_read_b64_tr_b16 v[240:241], v245 offset:2560
	ds_read_b64_tr_b16 v[128:129], v245 offset:4096
	ds_read_b64_tr_b16 v[130:131], v245 offset:6144
	ds_read_b64_tr_b16 v[132:133], v245 offset:4608
	ds_read_b64_tr_b16 v[134:135], v245 offset:6656
	v_add_f32_e32 v246, v140, v246
	v_add_f32_e32 v246, v141, v246
	v_add_f32_e32 v246, v142, v246
	v_add_f32_e32 v246, v143, v246
	v_cvt_pk_bf16_f32 v230, v136, v137
	v_cvt_pk_bf16_f32 v231, v138, v139
	v_cvt_pk_bf16_f32 v232, v140, v141
	v_cvt_pk_bf16_f32 v233, v142, v143
	v_add_f32_e32 v215, v215, v246
	ds_read_b64_tr_b16 v[136:137], v245 offset:1024
	ds_read_b64_tr_b16 v[138:139], v245 offset:3072
	ds_read_b64_tr_b16 v[140:141], v245 offset:1536
	ds_read_b64_tr_b16 v[142:143], v245 offset:3584
	s_waitcnt lgkmcnt(8)
	v_mfma_f32_32x32x16_bf16 v[112:127], v[226:229], v[234:237], v[112:127]
	v_mfma_f32_32x32x16_bf16 v[96:111], v[226:229], v[238:241], v[96:111]
	s_add_i32 s41, s85, s24
	s_add_i32 m0, s41, 0x8000
	ds_read_b64_tr_b16 v[234:235], v245 offset:5120
	ds_read_b64_tr_b16 v[236:237], v245 offset:7168
	ds_read_b64_tr_b16 v[238:239], v245 offset:5632
	ds_read_b64_tr_b16 v[240:241], v245 offset:7680
	global_load_lds_dwordx4 v218, s[2:3] sc1
	s_waitcnt lgkmcnt(8)
	v_mfma_f32_32x32x16_bf16 v[112:127], v[230:233], v[128:131], v[112:127]
	v_mfma_f32_32x32x16_bf16 v[96:111], v[230:233], v[132:135], v[96:111]
	s_add_i32 s41, s85, s24
	s_add_i32 m0, s41, 0xa000
	ds_read_b64_tr_b16 v[128:129], v245 offset:16384
	ds_read_b64_tr_b16 v[130:131], v245 offset:18432
	ds_read_b64_tr_b16 v[132:133], v245 offset:16896
	ds_read_b64_tr_b16 v[134:135], v245 offset:18944
	global_load_lds_dwordx4 v217, s[2:3] sc1
	s_waitcnt lgkmcnt(8)
	v_mfma_f32_32x32x16_bf16 v[80:95], v[226:229], v[136:139], v[80:95]
	v_mfma_f32_32x32x16_bf16 v[64:79], v[226:229], v[140:143], v[64:79]
	s_add_i32 s41, s85, s24
	s_add_i32 m0, s41, 0xc000
	ds_read_b64_tr_b16 v[136:137], v245 offset:20480
	ds_read_b64_tr_b16 v[138:139], v245 offset:22528
	ds_read_b64_tr_b16 v[140:141], v245 offset:20992
	ds_read_b64_tr_b16 v[142:143], v245 offset:23040
	global_load_lds_dwordx4 v242, s[2:3] sc1
	s_waitcnt lgkmcnt(8)
	v_mfma_f32_32x32x16_bf16 v[80:95], v[230:233], v[234:237], v[80:95]
	v_mfma_f32_32x32x16_bf16 v[64:79], v[230:233], v[238:241], v[64:79]
	s_add_i32 s41, s85, s24
	s_add_i32 m0, s41, 0xe000
	ds_read_b64_tr_b16 v[234:235], v245 offset:17408
	ds_read_b64_tr_b16 v[236:237], v245 offset:19456
	ds_read_b64_tr_b16 v[238:239], v245 offset:17920
	ds_read_b64_tr_b16 v[240:241], v245 offset:19968
	global_load_lds_dwordx4 v243, s[2:3] sc1
	s_waitcnt lgkmcnt(8)
	v_mfma_f32_32x32x16_bf16 v[48:63], v[226:229], v[128:131], v[48:63]
	v_mfma_f32_32x32x16_bf16 v[32:47], v[226:229], v[132:135], v[32:47]
	ds_read_b64_tr_b16 v[128:129], v245 offset:21504
	ds_read_b64_tr_b16 v[130:131], v245 offset:23552
	ds_read_b64_tr_b16 v[132:133], v245 offset:22016
	ds_read_b64_tr_b16 v[134:135], v245 offset:24064
	s_waitcnt lgkmcnt(8)
	v_mfma_f32_32x32x16_bf16 v[48:63], v[230:233], v[136:139], v[48:63]
	v_mfma_f32_32x32x16_bf16 v[32:47], v[230:233], v[140:143], v[32:47]
	s_waitcnt lgkmcnt(0)
	v_mfma_f32_32x32x16_bf16 v[16:31], v[226:229], v[234:237], v[16:31]
	s_waitcnt vmcnt(0)
	s_barrier
	s_add_u32 s86, s86, 0x4000
	s_addc_u32 s87, s87, 0
	s_add_u32 s2, s2, 0x8000
	s_addc_u32 s3, s3, 0
	v_mfma_f32_32x32x16_bf16 v[0:15], v[226:229], v[238:241], v[0:15]
	v_mfma_f32_32x32x16_bf16 v[16:31], v[230:233], v[128:131], v[16:31]
	s_add_i32 s84, s84, 0x8000
	s_cmp_eq_u32 s84, 0x18000
	s_cselect_b32 s84, 0, s84
	s_add_i32 s25, s25, 1
	s_cmpk_eq_i32 s25, 0x82
	v_mfma_f32_32x32x16_bf16 v[0:15], v[230:233], v[132:135], v[0:15]
	s_cbranch_scc0 .LBB0_1019
	s_barrier
	s_branch .Lattn_join_m0

; #define SBAR() __builtin_amdgcn_sched_barrier(0)
; #define PVR(S, DA, DB, vbase) do { S[0] = tr_read<v_rd_off(DA, 0, 0)>(vbase); S[1] = tr_read<v_rd_off(DA, 0, 1)>(vbase); S[2] = tr_read<v_rd_off(DB, 0, 0)>(vbase); S[3] = tr_read<v_rd_off(DB, 0, 1)>(vbase); \
;     S[4] = tr_read<v_rd_off(DA, 1, 0)>(vbase); S[5] = tr_read<v_rd_off(DA, 1, 1)>(vbase); S[6] = tr_read<v_rd_off(DB, 1, 0)>(vbase); S[7] = tr_read<v_rd_off(DB, 1, 1)>(vbase); } while (0)
; #define RAWBAR() do { asm volatile("s_waitcnt lgkmcnt(0)" ::: "memory"); __builtin_amdgcn_s_barrier(); asm volatile("" ::: "memory"); } while (0)
; #define RAWBAR() do { asm volatile("s_waitcnt lgkmcnt(0)" ::: "memory"); __builtin_amdgcn_s_barrier(); asm volatile("" ::: "memory"); } while (0)
; #define RAWBAR() do { asm volatile("s_waitcnt lgkmcnt(0)" ::: "memory"); __builtin_amdgcn_s_barrier(); asm volatile("" ::: "memory"); } while (0)
; #define RAWBAR() do { asm volatile("s_waitcnt lgkmcnt(0)" ::: "memory"); __builtin_amdgcn_s_barrier(); asm volatile("" ::: "memory"); } while (0)
; #define RAWBAR() do { asm volatile("s_waitcnt lgkmcnt(0)" ::: "memory"); __builtin_amdgcn_s_barrier(); asm volatile("" ::: "memory"); } while (0)
; template <int MODE> ...
;     ...
;   for (int j = 0; j < NT; ++j) {
;     const int buf = j & 1;
;     if (j + 1 < NT) { STAGE((j + 1) * KVBLK, buf ^ 1); }
;     const char* Kb = K_lds + buf * 16384;
;     f32x16 pe = {}, po = {};
; #pragma unroll
;     for (int d0 = 0; d0 < 8; d0 += 2) {
;       const bf16x8 k0 = *reinterpret_cast<const bf16x8*>(Kb + KSWZ(krow, (d0 * 16 + hi * 8) * 2));
;       const bf16x8 k1 = *reinterpret_cast<const bf16x8*>(Kb + KSWZ(krow, ((d0 + 1) * 16 + hi * 8) * 2));
;       pe = __builtin_amdgcn_mfma_f32_32x32x16_bf16(k0, qr[d0], pe, 0, 0, 0);
;       po = __builtin_amdgcn_mfma_f32_32x32x16_bf16(k1, qr[d0 + 1], po, 0, 0, 0); }
;     const int vo = vb0 + buf * 32768;
;     s16x4 R0_[8], R1_[8];
;     PVR(R0_, 0, 1, vo);
;     f32x16 p;
; #pragma unroll
;     for (int r = 0; r < 16; ++r) p[r] = __builtin_amdgcn_exp2f(fmaf(pe[r] + po[r], C, negMc));
;     float ps = 0.f;
; #pragma unroll
;     for (int r = 0; r < 16; ++r) ps += p[r];
;     lsum += ps;
;     const bf16x8 own0 = pk8(p, 0), own1 = pk8(p, 8);
;     SBAR();
;     PV_TAIL4(o, vo, vo + 16384, own0, own1);
;     asm volatile("s_waitcnt vmcnt(0)" ::: "memory");
;     RAWBAR();
;   }
.LattnB_m0:
	ds_read_b128 v[226:229], v225 offset:16384
	ds_read_b128 v[230:233], v223 offset:16384
	ds_read_b128 v[234:237], v222 offset:16384
	ds_read_b128 v[238:241], v221 offset:16384
	v_exp_f32_e32 v144, v144
	v_exp_f32_e32 v145, v145
	v_exp_f32_e32 v146, v146
	v_exp_f32_e32 v147, v147
	s_waitcnt lgkmcnt(2)
	v_mfma_f32_32x32x16_bf16 v[128:143], v[226:229], v[188:191], 0
	v_mfma_f32_32x32x16_bf16 v[128:143], v[230:233], v[184:187], v[128:143]
	ds_read_b128 v[226:229], v202 offset:16384
	ds_read_b128 v[230:233], v203 offset:16384
	v_exp_f32_e32 v148, v148
	v_exp_f32_e32 v149, v149
	v_exp_f32_e32 v150, v150
	v_exp_f32_e32 v151, v151
	v_add_f32_e32 v246, v144, v145
	v_add_f32_e32 v246, v146, v246
	v_add_f32_e32 v246, v147, v246
	s_waitcnt lgkmcnt(2)
	v_mfma_f32_32x32x16_bf16 v[128:143], v[234:237], v[180:183], v[128:143]
	v_mfma_f32_32x32x16_bf16 v[128:143], v[238:241], v[176:179], v[128:143]
	ds_read_b128 v[234:237], v204 offset:16384
	ds_read_b128 v[238:241], v205 offset:16384
	v_exp_f32_e32 v152, v152
	v_exp_f32_e32 v153, v153
	v_exp_f32_e32 v154, v154
	v_exp_f32_e32 v155, v155
	v_add_f32_e32 v246, v148, v246
	v_add_f32_e32 v246, v149, v246
	v_add_f32_e32 v246, v150, v246
	v_add_f32_e32 v246, v151, v246
	s_waitcnt lgkmcnt(2)
	v_mfma_f32_32x32x16_bf16 v[128:143], v[226:229], v[172:175], v[128:143]
	v_mfma_f32_32x32x16_bf16 v[128:143], v[230:233], v[168:171], v[128:143]
	v_exp_f32_e32 v156, v156
	v_exp_f32_e32 v157, v157
	v_exp_f32_e32 v158, v158
	v_exp_f32_e32 v159, v159
	v_add_f32_e32 v246, v152, v246
	v_add_f32_e32 v246, v153, v246
	v_add_f32_e32 v246, v154, v246
	v_add_f32_e32 v246, v155, v246
	v_cvt_pk_bf16_f32 v226, v144, v145
	v_cvt_pk_bf16_f32 v227, v146, v147
	v_cvt_pk_bf16_f32 v228, v148, v149
	v_cvt_pk_bf16_f32 v229, v150, v151
	s_waitcnt lgkmcnt(0)
	v_mfma_f32_32x32x16_bf16 v[128:143], v[234:237], v[164:167], v[128:143]
	v_mfma_f32_32x32x16_bf16 v[128:143], v[238:241], v[160:163], v[128:143]
	s_waitcnt vmcnt(0)
	s_barrier
	s_add_u32 s86, s86, 0x4000
	s_addc_u32 s87, s87, 0
	s_add_u32 s2, s2, 0x8000
	s_addc_u32 s3, s3, 0
	v_add_u32_e32 v245, s84, v214
	s_sub_u32 s85, s84, 0x8000
	s_cmp_eq_u32 s84, 0
	s_cselect_b32 s85, 0x10000, s85
	ds_read_b64_tr_b16 v[234:235], v245 offset:0
	ds_read_b64_tr_b16 v[236:237], v245 offset:2048
	ds_read_b64_tr_b16 v[238:239], v245 offset:512
	ds_read_b64_tr_b16 v[240:241], v245 offset:2560
	ds_read_b64_tr_b16 v[144:145], v245 offset:4096
	ds_read_b64_tr_b16 v[146:147], v245 offset:6144
	ds_read_b64_tr_b16 v[148:149], v245 offset:4608
	ds_read_b64_tr_b16 v[150:151], v245 offset:6656
	v_add_f32_e32 v246, v156, v246
	v_add_f32_e32 v246, v157, v246
	v_add_f32_e32 v246, v158, v246
	v_add_f32_e32 v246, v159, v246
	v_cvt_pk_bf16_f32 v230, v152, v153
	v_cvt_pk_bf16_f32 v231, v154, v155
	v_cvt_pk_bf16_f32 v232, v156, v157
	v_cvt_pk_bf16_f32 v233, v158, v159
	v_add_f32_e32 v215, v215, v246
	ds_read_b64_tr_b16 v[152:153], v245 offset:1024
	ds_read_b64_tr_b16 v[154:155], v245 offset:3072
	ds_read_b64_tr_b16 v[156:157], v245 offset:1536
	ds_read_b64_tr_b16 v[158:159], v245 offset:3584
	s_waitcnt lgkmcnt(8)
	v_mfma_f32_32x32x16_bf16 v[112:127], v[226:229], v[234:237], v[112:127]
	v_mfma_f32_32x32x16_bf16 v[96:111], v[226:229], v[238:241], v[96:111]
	s_add_i32 s41, s85, s24
	s_add_i32 m0, s41, 0x8000
	ds_read_b64_tr_b16 v[234:235], v245 offset:5120
	ds_read_b64_tr_b16 v[236:237], v245 offset:7168
	ds_read_b64_tr_b16 v[238:239], v245 offset:5632
	ds_read_b64_tr_b16 v[240:241], v245 offset:7680
	global_load_lds_dwordx4 v218, s[2:3] sc1
	s_waitcnt lgkmcnt(8)
	v_mfma_f32_32x32x16_bf16 v[112:127], v[230:233], v[144:147], v[112:127]
	v_mfma_f32_32x32x16_bf16 v[96:111], v[230:233], v[148:151], v[96:111]
	s_add_i32 s41, s85, s24
	s_add_i32 m0, s41, 0xa000
	ds_read_b64_tr_b16 v[144:145], v245 offset:16384
	ds_read_b64_tr_b16 v[146:147], v245 offset:18432
	ds_read_b64_tr_b16 v[148:149], v245 offset:16896
	ds_read_b64_tr_b16 v[150:151], v245 offset:18944
	global_load_lds_dwordx4 v217, s[2:3] sc1
	s_waitcnt lgkmcnt(8)
	v_mfma_f32_32x32x16_bf16 v[80:95], v[226:229], v[152:155], v[80:95]
	v_mfma_f32_32x32x16_bf16 v[64:79], v[226:229], v[156:159], v[64:79]
	s_add_i32 s41, s85, s24
	s_add_i32 m0, s41, 0xc000
	ds_read_b64_tr_b16 v[152:153], v245 offset:20480
	ds_read_b64_tr_b16 v[154:155], v245 offset:22528
	ds_read_b64_tr_b16 v[156:157], v245 offset:20992
	ds_read_b64_tr_b16 v[158:159], v245 offset:23040
	global_load_lds_dwordx4 v242, s[2:3] sc1
	s_waitcnt lgkmcnt(8)
	v_mfma_f32_32x32x16_bf16 v[80:95], v[230:233], v[234:237], v[80:95]
	v_mfma_f32_32x32x16_bf16 v[64:79], v[230:233], v[238:241], v[64:79]
	s_add_i32 s41, s85, s24
	s_add_i32 m0, s41, 0xe000
	ds_read_b64_tr_b16 v[234:235], v245 offset:17408
	ds_read_b64_tr_b16 v[236:237], v245 offset:19456
	ds_read_b64_tr_b16 v[238:239], v245 offset:17920
	ds_read_b64_tr_b16 v[240:241], v245 offset:19968
	global_load_lds_dwordx4 v243, s[2:3] sc1
	s_waitcnt lgkmcnt(8)
	v_mfma_f32_32x32x16_bf16 v[48:63], v[226:229], v[144:147], v[48:63]
	v_mfma_f32_32x32x16_bf16 v[32:47], v[226:229], v[148:151], v[32:47]
	s_add_i32 m0, s24, 0x4000
	ds_read_b64_tr_b16 v[144:145], v245 offset:21504
	ds_read_b64_tr_b16 v[146:147], v245 offset:23552
	ds_read_b64_tr_b16 v[148:149], v245 offset:22016
	ds_read_b64_tr_b16 v[150:151], v245 offset:24064
	global_load_lds_dwordx4 v220, s[86:87] sc1
	s_waitcnt lgkmcnt(8)
	v_mfma_f32_32x32x16_bf16 v[48:63], v[230:233], v[152:155], v[48:63]
	v_mfma_f32_32x32x16_bf16 v[32:47], v[230:233], v[156:159], v[32:47]
	s_add_i32 m0, s24, 0x6000
	s_nop 0
	global_load_lds_dwordx4 v219, s[86:87] sc1
	s_waitcnt lgkmcnt(0)
; #define SBAR() __builtin_amdgcn_sched_barrier(0)
; #define PVR(S, DA, DB, vbase) do { S[0] = tr_read<v_rd_off(DA, 0, 0)>(vbase); S[1] = tr_read<v_rd_off(DA, 0, 1)>(vbase); S[2] = tr_read<v_rd_off(DB, 0, 0)>(vbase); S[3] = tr_read<v_rd_off(DB, 0, 1)>(vbase); \
;     S[4] = tr_read<v_rd_off(DA, 1, 0)>(vbase); S[5] = tr_read<v_rd_off(DA, 1, 1)>(vbase); S[6] = tr_read<v_rd_off(DB, 1, 0)>(vbase); S[7] = tr_read<v_rd_off(DB, 1, 1)>(vbase); } while (0)
; #define RAWBAR() do { asm volatile("s_waitcnt lgkmcnt(0)" ::: "memory"); __builtin_amdgcn_s_barrier(); asm volatile("" ::: "memory"); } while (0)
; #define RAWBAR() do { asm volatile("s_waitcnt lgkmcnt(0)" ::: "memory"); __builtin_amdgcn_s_barrier(); asm volatile("" ::: "memory"); } while (0)
; #define RAWBAR() do { asm volatile("s_waitcnt lgkmcnt(0)" ::: "memory"); __builtin_amdgcn_s_barrier(); asm volatile("" ::: "memory"); } while (0)
; #define RAWBAR() do { asm volatile("s_waitcnt lgkmcnt(0)" ::: "memory"); __builtin_amdgcn_s_barrier(); asm volatile("" ::: "memory"); } while (0)
; #define RAWBAR() do { asm volatile("s_waitcnt lgkmcnt(0)" ::: "memory"); __builtin_amdgcn_s_barrier(); asm volatile("" ::: "memory"); } while (0)
; template <int MODE> ...
;     ...
;   for (int j = 0; j < NT; ++j) {
;     const int buf = j & 1;
;     if (j + 1 < NT) { STAGE((j + 1) * KVBLK, buf ^ 1); }
;     const char* Kb = K_lds + buf * 16384;
;     f32x16 pe = {}, po = {};
; #pragma unroll
;     for (int d0 = 0; d0 < 8; d0 += 2) {
;       const bf16x8 k0 = *reinterpret_cast<const bf16x8*>(Kb + KSWZ(krow, (d0 * 16 + hi * 8) * 2));
;       const bf16x8 k1 = *reinterpret_cast<const bf16x8*>(Kb + KSWZ(krow, ((d0 + 1) * 16 + hi * 8) * 2));
;       pe = __builtin_amdgcn_mfma_f32_32x32x16_bf16(k0, qr[d0], pe, 0, 0, 0);
;       po = __builtin_amdgcn_mfma_f32_32x32x16_bf16(k1, qr[d0 + 1], po, 0, 0, 0); }
;     const int vo = vb0 + buf * 32768;
;     s16x4 R0_[8], R1_[8];
;     PVR(R0_, 0, 1, vo);
;     f32x16 p;
; #pragma unroll
;     for (int r = 0; r < 16; ++r) p[r] = __builtin_amdgcn_exp2f(fmaf(pe[r] + po[r], C, negMc));
;     float ps = 0.f;
; #pragma unroll
;     for (int r = 0; r < 16; ++r) ps += p[r];
;     lsum += ps;
;     const bf16x8 own0 = pk8(p, 0), own1 = pk8(p, 8);
;     SBAR();
;     PV_TAIL4(o, vo, vo + 16384, own0, own1);
;     asm volatile("s_waitcnt vmcnt(0)" ::: "memory");
;     RAWBAR();
;   }
	v_mfma_f32_32x32x16_bf16 v[16:31], v[226:229], v[234:237], v[16:31]
	v_mfma_f32_32x32x16_bf16 v[0:15], v[226:229], v[238:241], v[0:15]
	v_mfma_f32_32x32x16_bf16 v[16:31], v[230:233], v[144:147], v[16:31]
	s_add_i32 s84, s84, 0x8000
	s_cmp_eq_u32 s84, 0x18000
	s_cselect_b32 s84, 0, s84
	v_mfma_f32_32x32x16_bf16 v[0:15], v[230:233], v[148:151], v[0:15]
	ds_read_b128 v[226:229], v225 offset:0
	ds_read_b128 v[230:233], v223 offset:0
	ds_read_b128 v[234:237], v222 offset:0
	ds_read_b128 v[238:241], v221 offset:0
	v_exp_f32_e32 v128, v128
	v_exp_f32_e32 v129, v129
	v_exp_f32_e32 v130, v130
	v_exp_f32_e32 v131, v131
	s_waitcnt lgkmcnt(2)
	v_mfma_f32_32x32x16_bf16 v[144:159], v[226:229], v[188:191], 0
	v_mfma_f32_32x32x16_bf16 v[144:159], v[230:233], v[184:187], v[144:159]
	ds_read_b128 v[226:229], v202 offset:0
	ds_read_b128 v[230:233], v203 offset:0
	v_exp_f32_e32 v132, v132
	v_exp_f32_e32 v133, v133
	v_exp_f32_e32 v134, v134
	v_exp_f32_e32 v135, v135
	v_add_f32_e32 v246, v128, v129
	v_add_f32_e32 v246, v130, v246
	v_add_f32_e32 v246, v131, v246
	s_waitcnt lgkmcnt(2)
	v_mfma_f32_32x32x16_bf16 v[144:159], v[234:237], v[180:183], v[144:159]
	v_mfma_f32_32x32x16_bf16 v[144:159], v[238:241], v[176:179], v[144:159]
	ds_read_b128 v[234:237], v204 offset:0
	ds_read_b128 v[238:241], v205 offset:0
	v_exp_f32_e32 v136, v136
	v_exp_f32_e32 v137, v137
	v_exp_f32_e32 v138, v138
	v_exp_f32_e32 v139, v139
	v_add_f32_e32 v246, v132, v246
	v_add_f32_e32 v246, v133, v246
	v_add_f32_e32 v246, v134, v246
	v_add_f32_e32 v246, v135, v246
	s_waitcnt lgkmcnt(2)
	v_mfma_f32_32x32x16_bf16 v[144:159], v[226:229], v[172:175], v[144:159]
	v_mfma_f32_32x32x16_bf16 v[144:159], v[230:233], v[168:171], v[144:159]
	v_exp_f32_e32 v140, v140
	v_exp_f32_e32 v141, v141
	v_exp_f32_e32 v142, v142
	v_exp_f32_e32 v143, v143
	v_add_f32_e32 v246, v136, v246
	v_add_f32_e32 v246, v137, v246
	v_add_f32_e32 v246, v138, v246
	v_add_f32_e32 v246, v139, v246
	v_cvt_pk_bf16_f32 v226, v128, v129
	v_cvt_pk_bf16_f32 v227, v130, v131
	v_cvt_pk_bf16_f32 v228, v132, v133
	v_cvt_pk_bf16_f32 v229, v134, v135
	s_waitcnt lgkmcnt(0)
	v_mfma_f32_32x32x16_bf16 v[144:159], v[234:237], v[164:167], v[144:159]
	v_mfma_f32_32x32x16_bf16 v[144:159], v[238:241], v[160:163], v[144:159]
	s_waitcnt vmcnt(0)
	s_barrier
	s_add_u32 s86, s86, 0x4000
	s_addc_u32 s87, s87, 0
	s_add_u32 s2, s2, 0x8000
	s_addc_u32 s3, s3, 0
	v_add_u32_e32 v245, s84, v214
	s_sub_u32 s85, s84, 0x8000
	s_cmp_eq_u32 s84, 0
	s_cselect_b32 s85, 0x10000, s85
	ds_read_b64_tr_b16 v[234:235], v245 offset:0
	ds_read_b64_tr_b16 v[236:237], v245 offset:2048
	ds_read_b64_tr_b16 v[238:239], v245 offset:512
	ds_read_b64_tr_b16 v[240:241], v245 offset:2560
	ds_read_b64_tr_b16 v[128:129], v245 offset:4096
	ds_read_b64_tr_b16 v[130:131], v245 offset:6144
	ds_read_b64_tr_b16 v[132:133], v245 offset:4608
	ds_read_b64_tr_b16 v[134:135], v245 offset:6656
	v_add_f32_e32 v246, v140, v246
	v_add_f32_e32 v246, v141, v246
	v_add_f32_e32 v246, v142, v246
	v_add_f32_e32 v246, v143, v246
	v_cvt_pk_bf16_f32 v230, v136, v137
	v_cvt_pk_bf16_f32 v231, v138, v139
	v_cvt_pk_bf16_f32 v232, v140, v141
	v_cvt_pk_bf16_f32 v233, v142, v143
	v_add_f32_e32 v215, v215, v246
	ds_read_b64_tr_b16 v[136:137], v245 offset:1024
	ds_read_b64_tr_b16 v[138:139], v245 offset:3072
	ds_read_b64_tr_b16 v[140:141], v245 offset:1536
	ds_read_b64_tr_b16 v[142:143], v245 offset:3584
	s_waitcnt lgkmcnt(8)
	v_mfma_f32_32x32x16_bf16 v[112:127], v[226:229], v[234:237], v[112:127]
	v_mfma_f32_32x32x16_bf16 v[96:111], v[226:229], v[238:241], v[96:111]
	s_add_i32 s41, s85, s24
	s_add_i32 m0, s41, 0x8000
	ds_read_b64_tr_b16 v[234:235], v245 offset:5120
	ds_read_b64_tr_b16 v[236:237], v245 offset:7168
	ds_read_b64_tr_b16 v[238:239], v245 offset:5632
	ds_read_b64_tr_b16 v[240:241], v245 offset:7680
	global_load_lds_dwordx4 v218, s[2:3] sc1
	s_waitcnt lgkmcnt(8)
	v_mfma_f32_32x32x16_bf16 v[112:127], v[230:233], v[128:131], v[112:127]
	v_mfma_f32_32x32x16_bf16 v[96:111], v[230:233], v[132:135], v[96:111]
	s_add_i32 s41, s85, s24
	s_add_i32 m0, s41, 0xa000
	ds_read_b64_tr_b16 v[128:129], v245 offset:16384
	ds_read_b64_tr_b16 v[130:131], v245 offset:18432
	ds_read_b64_tr_b16 v[132:133], v245 offset:16896
	ds_read_b64_tr_b16 v[134:135], v245 offset:18944
	global_load_lds_dwordx4 v217, s[2:3] sc1
	s_waitcnt lgkmcnt(8)
	v_mfma_f32_32x32x16_bf16 v[80:95], v[226:229], v[136:139], v[80:95]
	v_mfma_f32_32x32x16_bf16 v[64:79], v[226:229], v[140:143], v[64:79]
	s_add_i32 s41, s85, s24
	s_add_i32 m0, s41, 0xc000
	ds_read_b64_tr_b16 v[136:137], v245 offset:20480
	ds_read_b64_tr_b16 v[138:139], v245 offset:22528
	ds_read_b64_tr_b16 v[140:141], v245 offset:20992
	ds_read_b64_tr_b16 v[142:143], v245 offset:23040
	global_load_lds_dwordx4 v242, s[2:3] sc1
	s_waitcnt lgkmcnt(8)
	v_mfma_f32_32x32x16_bf16 v[80:95], v[230:233], v[234:237], v[80:95]
	v_mfma_f32_32x32x16_bf16 v[64:79], v[230:233], v[238:241], v[64:79]
	s_add_i32 s41, s85, s24
	s_add_i32 m0, s41, 0xe000
	ds_read_b64_tr_b16 v[234:235], v245 offset:17408
	ds_read_b64_tr_b16 v[236:237], v245 offset:19456
	ds_read_b64_tr_b16 v[238:239], v245 offset:17920
	ds_read_b64_tr_b16 v[240:241], v245 offset:19968
	global_load_lds_dwordx4 v243, s[2:3] sc1
	s_waitcnt lgkmcnt(8)
	v_mfma_f32_32x32x16_bf16 v[48:63], v[226:229], v[128:131], v[48:63]
	v_mfma_f32_32x32x16_bf16 v[32:47], v[226:229], v[132:135], v[32:47]
	s_mov_b32 m0, s24
	ds_read_b64_tr_b16 v[128:129], v245 offset:21504
	ds_read_b64_tr_b16 v[130:131], v245 offset:23552
	ds_read_b64_tr_b16 v[132:133], v245 offset:22016
	ds_read_b64_tr_b16 v[134:135], v245 offset:24064
	global_load_lds_dwordx4 v220, s[86:87] sc1
	s_waitcnt lgkmcnt(8)
	v_mfma_f32_32x32x16_bf16 v[48:63], v[230:233], v[136:139], v[48:63]
	v_mfma_f32_32x32x16_bf16 v[32:47], v[230:233], v[140:143], v[32:47]
	s_add_i32 m0, s24, 0x2000
	s_nop 0
	global_load_lds_dwordx4 v219, s[86:87] sc1
	s_waitcnt lgkmcnt(0)
	v_mfma_f32_32x32x16_bf16 v[16:31], v[226:229], v[234:237], v[16:31]
	v_mfma_f32_32x32x16_bf16 v[0:15], v[226:229], v[238:241], v[0:15]
	v_mfma_f32_32x32x16_bf16 v[16:31], v[230:233], v[128:131], v[16:31]
	s_add_i32 s84, s84, 0x8000
	s_cmp_eq_u32 s84, 0x18000
	s_cselect_b32 s84, 0, s84
	s_add_i32 s25, s25, 1
	s_cmpk_eq_i32 s25, 0x82
	v_mfma_f32_32x32x16_bf16 v[0:15], v[230:233], v[132:135], v[0:15]
	s_cbranch_scc0 .LattnB_m0
	s_waitcnt vmcnt(0)
	s_barrier

; #define SBAR() __builtin_amdgcn_sched_barrier(0)
; #define PVR(S, DA, DB, vbase) do { S[0] = tr_read<v_rd_off(DA, 0, 0)>(vbase); S[1] = tr_read<v_rd_off(DA, 0, 1)>(vbase); S[2] = tr_read<v_rd_off(DB, 0, 0)>(vbase); S[3] = tr_read<v_rd_off(DB, 0, 1)>(vbase); \
;     S[4] = tr_read<v_rd_off(DA, 1, 0)>(vbase); S[5] = tr_read<v_rd_off(DA, 1, 1)>(vbase); S[6] = tr_read<v_rd_off(DB, 1, 0)>(vbase); S[7] = tr_read<v_rd_off(DB, 1, 1)>(vbase); } while (0)
; #define RAWBAR() do { asm volatile("s_waitcnt lgkmcnt(0)" ::: "memory"); __builtin_amdgcn_s_barrier(); asm volatile("" ::: "memory"); } while (0)
; #define RAWBAR() do { asm volatile("s_waitcnt lgkmcnt(0)" ::: "memory"); __builtin_amdgcn_s_barrier(); asm volatile("" ::: "memory"); } while (0)
; #define RAWBAR() do { asm volatile("s_waitcnt lgkmcnt(0)" ::: "memory"); __builtin_amdgcn_s_barrier(); asm volatile("" ::: "memory"); } while (0)
; #define RAWBAR() do { asm volatile("s_waitcnt lgkmcnt(0)" ::: "memory"); __builtin_amdgcn_s_barrier(); asm volatile("" ::: "memory"); } while (0)
; #define RAWBAR() do { asm volatile("s_waitcnt lgkmcnt(0)" ::: "memory"); __builtin_amdgcn_s_barrier(); asm volatile("" ::: "memory"); } while (0)
; template <int MODE> ...
;     ...
;   for (int j = 0; j < NT; ++j) {
;     const int buf = j & 1;
;     if (j + 1 < NT) { STAGE((j + 1) * KVBLK, buf ^ 1); }
;     const char* Kb = K_lds + buf * 16384;
;     f32x16 pe = {}, po = {};
; #pragma unroll
;     for (int d0 = 0; d0 < 8; d0 += 2) {
;       const bf16x8 k0 = *reinterpret_cast<const bf16x8*>(Kb + KSWZ(krow, (d0 * 16 + hi * 8) * 2));
;       const bf16x8 k1 = *reinterpret_cast<const bf16x8*>(Kb + KSWZ(krow, ((d0 + 1) * 16 + hi * 8) * 2));
;       pe = __builtin_amdgcn_mfma_f32_32x32x16_bf16(k0, qr[d0], pe, 0, 0, 0);
;       po = __builtin_amdgcn_mfma_f32_32x32x16_bf16(k1, qr[d0 + 1], po, 0, 0, 0); }
;     const int vo = vb0 + buf * 32768;
;     s16x4 R0_[8], R1_[8];
;     PVR(R0_, 0, 1, vo);
;     f32x16 p;
; #pragma unroll
;     for (int r = 0; r < 16; ++r) p[r] = __builtin_amdgcn_exp2f(fmaf(pe[r] + po[r], C, negMc));
;     float ps = 0.f;
; #pragma unroll
;     for (int r = 0; r < 16; ++r) ps += p[r];
;     lsum += ps;
;     const bf16x8 own0 = pk8(p, 0), own1 = pk8(p, 8);
;     SBAR();
;     PV_TAIL4(o, vo, vo + 16384, own0, own1);
;     asm volatile("s_waitcnt vmcnt(0)" ::: "memory");
;     RAWBAR();
;   }
.LBB0_1023:
	ds_read_b128 v[230:233], v229 offset:16384
	ds_read_b128 v[234:237], v228 offset:16384
	ds_read_b128 v[238:241], v227 offset:16384
	ds_read_b128 v[242:245], v226 offset:16384
	v_exp_f32_e32 v144, v144
	v_exp_f32_e32 v145, v145
	v_exp_f32_e32 v146, v146
	v_exp_f32_e32 v147, v147
	s_waitcnt lgkmcnt(2)
	v_mfma_f32_32x32x16_bf16 v[128:143], v[230:233], v[188:191], 0
	v_mfma_f32_32x32x16_bf16 v[128:143], v[234:237], v[184:187], v[128:143]
	ds_read_b128 v[230:233], v204 offset:16384
	ds_read_b128 v[234:237], v205 offset:16384
	s_mov_b32 m0, s34
	s_nop 0
	global_load_lds_dwordx4 v225, s[86:87] sc1
	v_exp_f32_e32 v148, v148
	v_exp_f32_e32 v149, v149
	v_exp_f32_e32 v150, v150
	v_exp_f32_e32 v151, v151
	v_add_f32_e32 v250, v144, v145
	v_add_f32_e32 v250, v146, v250
	v_add_f32_e32 v250, v147, v250
	s_waitcnt lgkmcnt(2)
	v_mfma_f32_32x32x16_bf16 v[128:143], v[238:241], v[180:183], v[128:143]
	v_mfma_f32_32x32x16_bf16 v[128:143], v[242:245], v[176:179], v[128:143]
	ds_read_b128 v[238:241], v206 offset:16384
	ds_read_b128 v[242:245], v207 offset:16384
	s_add_i32 m0, s34, 0x2000
	s_nop 0
	global_load_lds_dwordx4 v223, s[86:87] sc1
	v_exp_f32_e32 v152, v152
	v_exp_f32_e32 v153, v153
	v_exp_f32_e32 v154, v154
	v_exp_f32_e32 v155, v155
	v_add_f32_e32 v250, v148, v250
	v_add_f32_e32 v250, v149, v250
	v_add_f32_e32 v250, v150, v250
	v_add_f32_e32 v250, v151, v250
	s_waitcnt lgkmcnt(2)
	v_mfma_f32_32x32x16_bf16 v[128:143], v[230:233], v[172:175], v[128:143]
	v_mfma_f32_32x32x16_bf16 v[128:143], v[234:237], v[168:171], v[128:143]
	v_exp_f32_e32 v156, v156
	v_exp_f32_e32 v157, v157
	v_exp_f32_e32 v158, v158
	v_exp_f32_e32 v159, v159
	v_add_f32_e32 v250, v152, v250
	v_add_f32_e32 v250, v153, v250
	v_add_f32_e32 v250, v154, v250
	v_add_f32_e32 v250, v155, v250
	v_cvt_pk_bf16_f32 v230, v144, v145
	v_cvt_pk_bf16_f32 v231, v146, v147
	v_cvt_pk_bf16_f32 v232, v148, v149
	v_cvt_pk_bf16_f32 v233, v150, v151
	s_waitcnt lgkmcnt(0)
	v_mfma_f32_32x32x16_bf16 v[128:143], v[238:241], v[164:167], v[128:143]
	v_mfma_f32_32x32x16_bf16 v[128:143], v[242:245], v[160:163], v[128:143]
	v_add_u32_e32 v249, s84, v218
	s_add_i32 s85, s84, 0x8000
	s_cmp_eq_u32 s85, 0x18000
	s_cselect_b32 s85, 0, s85
	ds_read_b64_tr_b16 v[238:239], v249 offset:0
	ds_read_b64_tr_b16 v[240:241], v249 offset:2048
	ds_read_b64_tr_b16 v[242:243], v249 offset:512
	ds_read_b64_tr_b16 v[244:245], v249 offset:2560
	ds_read_b64_tr_b16 v[144:145], v249 offset:4096
	ds_read_b64_tr_b16 v[146:147], v249 offset:6144
	ds_read_b64_tr_b16 v[148:149], v249 offset:4608
	ds_read_b64_tr_b16 v[150:151], v249 offset:6656
	v_add_f32_e32 v250, v156, v250
	v_add_f32_e32 v250, v157, v250
	v_add_f32_e32 v250, v158, v250
	v_add_f32_e32 v250, v159, v250
	v_cvt_pk_bf16_f32 v234, v152, v153
	v_cvt_pk_bf16_f32 v235, v154, v155
	v_cvt_pk_bf16_f32 v236, v156, v157
	v_cvt_pk_bf16_f32 v237, v158, v159
	v_add_f32_e32 v219, v219, v250
	ds_read_b64_tr_b16 v[152:153], v249 offset:1024
	ds_read_b64_tr_b16 v[154:155], v249 offset:3072
	ds_read_b64_tr_b16 v[156:157], v249 offset:1536
	ds_read_b64_tr_b16 v[158:159], v249 offset:3584
	s_waitcnt lgkmcnt(8)
	v_mfma_f32_32x32x16_bf16 v[112:127], v[230:233], v[238:241], v[112:127]
	v_mfma_f32_32x32x16_bf16 v[96:111], v[230:233], v[242:245], v[96:111]
	s_add_i32 s30, s85, s34
	s_add_i32 m0, s30, 0x8000
	ds_read_b64_tr_b16 v[238:239], v249 offset:5120
	ds_read_b64_tr_b16 v[240:241], v249 offset:7168
	ds_read_b64_tr_b16 v[242:243], v249 offset:5632
	ds_read_b64_tr_b16 v[244:245], v249 offset:7680
	global_load_lds_dwordx4 v222, s[2:3] sc1
	s_waitcnt lgkmcnt(8)
	v_mfma_f32_32x32x16_bf16 v[112:127], v[234:237], v[144:147], v[112:127]
	v_mfma_f32_32x32x16_bf16 v[96:111], v[234:237], v[148:151], v[96:111]
	s_add_i32 s30, s85, s34
	s_add_i32 m0, s30, 0xa000
	ds_read_b64_tr_b16 v[144:145], v249 offset:16384
	ds_read_b64_tr_b16 v[146:147], v249 offset:18432
	ds_read_b64_tr_b16 v[148:149], v249 offset:16896
	ds_read_b64_tr_b16 v[150:151], v249 offset:18944
	global_load_lds_dwordx4 v221, s[2:3] sc1
	s_waitcnt lgkmcnt(8)
	v_mfma_f32_32x32x16_bf16 v[80:95], v[230:233], v[152:155], v[80:95]
	v_mfma_f32_32x32x16_bf16 v[64:79], v[230:233], v[156:159], v[64:79]
	s_add_i32 s30, s85, s34
	s_add_i32 m0, s30, 0xc000
	ds_read_b64_tr_b16 v[152:153], v249 offset:20480
	ds_read_b64_tr_b16 v[154:155], v249 offset:22528
	ds_read_b64_tr_b16 v[156:157], v249 offset:20992
	ds_read_b64_tr_b16 v[158:159], v249 offset:23040
	global_load_lds_dwordx4 v246, s[2:3] sc1
	s_waitcnt lgkmcnt(8)
	v_mfma_f32_32x32x16_bf16 v[80:95], v[234:237], v[238:241], v[80:95]
	v_mfma_f32_32x32x16_bf16 v[64:79], v[234:237], v[242:245], v[64:79]
	s_add_i32 s30, s85, s34
	s_add_i32 m0, s30, 0xe000
	ds_read_b64_tr_b16 v[238:239], v249 offset:17408
	ds_read_b64_tr_b16 v[240:241], v249 offset:19456
	ds_read_b64_tr_b16 v[242:243], v249 offset:17920
	ds_read_b64_tr_b16 v[244:245], v249 offset:19968
	global_load_lds_dwordx4 v247, s[2:3] sc1
	s_waitcnt lgkmcnt(8)
	v_mfma_f32_32x32x16_bf16 v[32:47], v[230:233], v[144:147], v[32:47]
	v_mfma_f32_32x32x16_bf16 v[16:31], v[230:233], v[148:151], v[16:31]
	ds_read_b64_tr_b16 v[144:145], v249 offset:21504
	ds_read_b64_tr_b16 v[146:147], v249 offset:23552
	ds_read_b64_tr_b16 v[148:149], v249 offset:22016
	ds_read_b64_tr_b16 v[150:151], v249 offset:24064
	s_waitcnt lgkmcnt(8)
	v_mfma_f32_32x32x16_bf16 v[32:47], v[234:237], v[152:155], v[32:47]
	v_mfma_f32_32x32x16_bf16 v[16:31], v[234:237], v[156:159], v[16:31]
	s_waitcnt lgkmcnt(0)
	v_mfma_f32_32x32x16_bf16 v[48:63], v[230:233], v[238:241], v[48:63]
	s_waitcnt vmcnt(0)
	s_barrier
; #define SBAR() __builtin_amdgcn_sched_barrier(0)
; #define PVR(S, DA, DB, vbase) do { S[0] = tr_read<v_rd_off(DA, 0, 0)>(vbase); S[1] = tr_read<v_rd_off(DA, 0, 1)>(vbase); S[2] = tr_read<v_rd_off(DB, 0, 0)>(vbase); S[3] = tr_read<v_rd_off(DB, 0, 1)>(vbase); \
;     S[4] = tr_read<v_rd_off(DA, 1, 0)>(vbase); S[5] = tr_read<v_rd_off(DA, 1, 1)>(vbase); S[6] = tr_read<v_rd_off(DB, 1, 0)>(vbase); S[7] = tr_read<v_rd_off(DB, 1, 1)>(vbase); } while (0)
; #define RAWBAR() do { asm volatile("s_waitcnt lgkmcnt(0)" ::: "memory"); __builtin_amdgcn_s_barrier(); asm volatile("" ::: "memory"); } while (0)
; #define RAWBAR() do { asm volatile("s_waitcnt lgkmcnt(0)" ::: "memory"); __builtin_amdgcn_s_barrier(); asm volatile("" ::: "memory"); } while (0)
; #define RAWBAR() do { asm volatile("s_waitcnt lgkmcnt(0)" ::: "memory"); __builtin_amdgcn_s_barrier(); asm volatile("" ::: "memory"); } while (0)
; #define RAWBAR() do { asm volatile("s_waitcnt lgkmcnt(0)" ::: "memory"); __builtin_amdgcn_s_barrier(); asm volatile("" ::: "memory"); } while (0)
; #define RAWBAR() do { asm volatile("s_waitcnt lgkmcnt(0)" ::: "memory"); __builtin_amdgcn_s_barrier(); asm volatile("" ::: "memory"); } while (0)
; template <int MODE> ...
;     ...
;   for (int j = 0; j < NT; ++j) {
;     const int buf = j & 1;
;     if (j + 1 < NT) { STAGE((j + 1) * KVBLK, buf ^ 1); }
;     const char* Kb = K_lds + buf * 16384;
;     f32x16 pe = {}, po = {};
; #pragma unroll
;     for (int d0 = 0; d0 < 8; d0 += 2) {
;       const bf16x8 k0 = *reinterpret_cast<const bf16x8*>(Kb + KSWZ(krow, (d0 * 16 + hi * 8) * 2));
;       const bf16x8 k1 = *reinterpret_cast<const bf16x8*>(Kb + KSWZ(krow, ((d0 + 1) * 16 + hi * 8) * 2));
;       pe = __builtin_amdgcn_mfma_f32_32x32x16_bf16(k0, qr[d0], pe, 0, 0, 0);
;       po = __builtin_amdgcn_mfma_f32_32x32x16_bf16(k1, qr[d0 + 1], po, 0, 0, 0); }
;     const int vo = vb0 + buf * 32768;
;     s16x4 R0_[8], R1_[8];
;     PVR(R0_, 0, 1, vo);
;     f32x16 p;
; #pragma unroll
;     for (int r = 0; r < 16; ++r) p[r] = __builtin_amdgcn_exp2f(fmaf(pe[r] + po[r], C, negMc));
;     float ps = 0.f;
; #pragma unroll
;     for (int r = 0; r < 16; ++r) ps += p[r];
;     lsum += ps;
;     const bf16x8 own0 = pk8(p, 0), own1 = pk8(p, 8);
;     SBAR();
;     PV_TAIL4(o, vo, vo + 16384, own0, own1);
;     asm volatile("s_waitcnt vmcnt(0)" ::: "memory");
;     RAWBAR();
;   }
	s_add_u32 s86, s86, 0x4000
	s_addc_u32 s87, s87, 0
	s_add_u32 s2, s2, 0x8000
	s_addc_u32 s3, s3, 0
	v_mfma_f32_32x32x16_bf16 v[0:15], v[230:233], v[242:245], v[0:15]
	v_mfma_f32_32x32x16_bf16 v[48:63], v[234:237], v[144:147], v[48:63]
	s_add_i32 s84, s84, 0x8000
	s_cmp_eq_u32 s84, 0x18000
	s_cselect_b32 s84, 0, s84
	v_mfma_f32_32x32x16_bf16 v[0:15], v[234:237], v[148:151], v[0:15]
	ds_read_b128 v[230:233], v229 offset:0
	ds_read_b128 v[234:237], v228 offset:0
	ds_read_b128 v[238:241], v227 offset:0
	ds_read_b128 v[242:245], v226 offset:0
	v_exp_f32_e32 v128, v128
	v_exp_f32_e32 v129, v129
	v_exp_f32_e32 v130, v130
	v_exp_f32_e32 v131, v131
	s_waitcnt lgkmcnt(2)
	v_mfma_f32_32x32x16_bf16 v[144:159], v[230:233], v[188:191], 0
	v_mfma_f32_32x32x16_bf16 v[144:159], v[234:237], v[184:187], v[144:159]
	ds_read_b128 v[230:233], v204 offset:0
	ds_read_b128 v[234:237], v205 offset:0
	s_add_i32 m0, s34, 0x4000
	s_nop 0
	global_load_lds_dwordx4 v225, s[86:87] sc1
	v_exp_f32_e32 v132, v132
	v_exp_f32_e32 v133, v133
	v_exp_f32_e32 v134, v134
	v_exp_f32_e32 v135, v135
	v_add_f32_e32 v250, v128, v129
	v_add_f32_e32 v250, v130, v250
	v_add_f32_e32 v250, v131, v250
	s_waitcnt lgkmcnt(2)
	v_mfma_f32_32x32x16_bf16 v[144:159], v[238:241], v[180:183], v[144:159]
	v_mfma_f32_32x32x16_bf16 v[144:159], v[242:245], v[176:179], v[144:159]
	ds_read_b128 v[238:241], v206 offset:0
	ds_read_b128 v[242:245], v207 offset:0
	s_add_i32 m0, s34, 0x6000
	s_nop 0
	global_load_lds_dwordx4 v223, s[86:87] sc1
	v_exp_f32_e32 v136, v136
	v_exp_f32_e32 v137, v137
	v_exp_f32_e32 v138, v138
	v_exp_f32_e32 v139, v139
	v_add_f32_e32 v250, v132, v250
	v_add_f32_e32 v250, v133, v250
	v_add_f32_e32 v250, v134, v250
	v_add_f32_e32 v250, v135, v250
	s_waitcnt lgkmcnt(2)
	v_mfma_f32_32x32x16_bf16 v[144:159], v[230:233], v[172:175], v[144:159]
	v_mfma_f32_32x32x16_bf16 v[144:159], v[234:237], v[168:171], v[144:159]
	v_exp_f32_e32 v140, v140
	v_exp_f32_e32 v141, v141
	v_exp_f32_e32 v142, v142
	v_exp_f32_e32 v143, v143
	v_add_f32_e32 v250, v136, v250
	v_add_f32_e32 v250, v137, v250
	v_add_f32_e32 v250, v138, v250
	v_add_f32_e32 v250, v139, v250
	v_cvt_pk_bf16_f32 v230, v128, v129
	v_cvt_pk_bf16_f32 v231, v130, v131
	v_cvt_pk_bf16_f32 v232, v132, v133
	v_cvt_pk_bf16_f32 v233, v134, v135
	s_waitcnt lgkmcnt(0)
	v_mfma_f32_32x32x16_bf16 v[144:159], v[238:241], v[164:167], v[144:159]
	v_mfma_f32_32x32x16_bf16 v[144:159], v[242:245], v[160:163], v[144:159]
	v_add_u32_e32 v249, s84, v218
	s_add_i32 s85, s84, 0x8000
	s_cmp_eq_u32 s85, 0x18000
	s_cselect_b32 s85, 0, s85
	ds_read_b64_tr_b16 v[238:239], v249 offset:0
	ds_read_b64_tr_b16 v[240:241], v249 offset:2048
	ds_read_b64_tr_b16 v[242:243], v249 offset:512
	ds_read_b64_tr_b16 v[244:245], v249 offset:2560
	ds_read_b64_tr_b16 v[128:129], v249 offset:4096
	ds_read_b64_tr_b16 v[130:131], v249 offset:6144
	ds_read_b64_tr_b16 v[132:133], v249 offset:4608
	ds_read_b64_tr_b16 v[134:135], v249 offset:6656
	v_add_f32_e32 v250, v140, v250
	v_add_f32_e32 v250, v141, v250
	v_add_f32_e32 v250, v142, v250
	v_add_f32_e32 v250, v143, v250
	v_cvt_pk_bf16_f32 v234, v136, v137
	v_cvt_pk_bf16_f32 v235, v138, v139
	v_cvt_pk_bf16_f32 v236, v140, v141
	v_cvt_pk_bf16_f32 v237, v142, v143
	v_add_f32_e32 v219, v219, v250
	ds_read_b64_tr_b16 v[136:137], v249 offset:1024
	ds_read_b64_tr_b16 v[138:139], v249 offset:3072
	ds_read_b64_tr_b16 v[140:141], v249 offset:1536
	ds_read_b64_tr_b16 v[142:143], v249 offset:3584
	s_waitcnt lgkmcnt(8)
	v_mfma_f32_32x32x16_bf16 v[112:127], v[230:233], v[238:241], v[112:127]
	v_mfma_f32_32x32x16_bf16 v[96:111], v[230:233], v[242:245], v[96:111]
	s_add_i32 s30, s85, s34
	s_add_i32 m0, s30, 0x8000
	ds_read_b64_tr_b16 v[238:239], v249 offset:5120
	ds_read_b64_tr_b16 v[240:241], v249 offset:7168
	ds_read_b64_tr_b16 v[242:243], v249 offset:5632
	ds_read_b64_tr_b16 v[244:245], v249 offset:7680
	global_load_lds_dwordx4 v222, s[2:3] sc1
	s_waitcnt lgkmcnt(8)
	v_mfma_f32_32x32x16_bf16 v[112:127], v[234:237], v[128:131], v[112:127]
	v_mfma_f32_32x32x16_bf16 v[96:111], v[234:237], v[132:135], v[96:111]
	s_add_i32 s30, s85, s34
	s_add_i32 m0, s30, 0xa000
	ds_read_b64_tr_b16 v[128:129], v249 offset:16384
	ds_read_b64_tr_b16 v[130:131], v249 offset:18432
	ds_read_b64_tr_b16 v[132:133], v249 offset:16896
	ds_read_b64_tr_b16 v[134:135], v249 offset:18944
	global_load_lds_dwordx4 v221, s[2:3] sc1
	s_waitcnt lgkmcnt(8)
	v_mfma_f32_32x32x16_bf16 v[80:95], v[230:233], v[136:139], v[80:95]
	v_mfma_f32_32x32x16_bf16 v[64:79], v[230:233], v[140:143], v[64:79]
	s_add_i32 s30, s85, s34
	s_add_i32 m0, s30, 0xc000
	ds_read_b64_tr_b16 v[136:137], v249 offset:20480
	ds_read_b64_tr_b16 v[138:139], v249 offset:22528
	ds_read_b64_tr_b16 v[140:141], v249 offset:20992
	ds_read_b64_tr_b16 v[142:143], v249 offset:23040
	global_load_lds_dwordx4 v246, s[2:3] sc1
	s_waitcnt lgkmcnt(8)
	v_mfma_f32_32x32x16_bf16 v[80:95], v[234:237], v[238:241], v[80:95]
	v_mfma_f32_32x32x16_bf16 v[64:79], v[234:237], v[242:245], v[64:79]
	s_add_i32 s30, s85, s34
	s_add_i32 m0, s30, 0xe000
	ds_read_b64_tr_b16 v[238:239], v249 offset:17408
	ds_read_b64_tr_b16 v[240:241], v249 offset:19456
	ds_read_b64_tr_b16 v[242:243], v249 offset:17920
	ds_read_b64_tr_b16 v[244:245], v249 offset:19968
	global_load_lds_dwordx4 v247, s[2:3] sc1
	s_waitcnt lgkmcnt(8)
	v_mfma_f32_32x32x16_bf16 v[32:47], v[230:233], v[128:131], v[32:47]
	v_mfma_f32_32x32x16_bf16 v[16:31], v[230:233], v[132:135], v[16:31]
	ds_read_b64_tr_b16 v[128:129], v249 offset:21504
	ds_read_b64_tr_b16 v[130:131], v249 offset:23552
	ds_read_b64_tr_b16 v[132:133], v249 offset:22016
	ds_read_b64_tr_b16 v[134:135], v249 offset:24064
	s_waitcnt lgkmcnt(8)
	v_mfma_f32_32x32x16_bf16 v[32:47], v[234:237], v[136:139], v[32:47]
	v_mfma_f32_32x32x16_bf16 v[16:31], v[234:237], v[140:143], v[16:31]
	s_waitcnt lgkmcnt(0)
	v_mfma_f32_32x32x16_bf16 v[48:63], v[230:233], v[238:241], v[48:63]
	s_waitcnt vmcnt(0)
	s_barrier
	s_add_u32 s86, s86, 0x4000
	s_addc_u32 s87, s87, 0
	s_add_u32 s2, s2, 0x8000
	s_addc_u32 s3, s3, 0
	v_mfma_f32_32x32x16_bf16 v[0:15], v[230:233], v[242:245], v[0:15]
	v_mfma_f32_32x32x16_bf16 v[48:63], v[234:237], v[128:131], v[48:63]
	s_add_i32 s84, s84, 0x8000
	s_cmp_eq_u32 s84, 0x18000
	s_cselect_b32 s84, 0, s84
	s_add_i32 s40, s40, 1
	s_cmpk_eq_i32 s40, 0x82
	v_mfma_f32_32x32x16_bf16 v[0:15], v[234:237], v[132:135], v[0:15]
	s_cbranch_scc0 .LBB0_1023
	s_barrier
	s_branch .Lattn_join_m1

; #define SBAR() __builtin_amdgcn_sched_barrier(0)
; #define PVR(S, DA, DB, vbase) do { S[0] = tr_read<v_rd_off(DA, 0, 0)>(vbase); S[1] = tr_read<v_rd_off(DA, 0, 1)>(vbase); S[2] = tr_read<v_rd_off(DB, 0, 0)>(vbase); S[3] = tr_read<v_rd_off(DB, 0, 1)>(vbase); \
;     S[4] = tr_read<v_rd_off(DA, 1, 0)>(vbase); S[5] = tr_read<v_rd_off(DA, 1, 1)>(vbase); S[6] = tr_read<v_rd_off(DB, 1, 0)>(vbase); S[7] = tr_read<v_rd_off(DB, 1, 1)>(vbase); } while (0)
; #define RAWBAR() do { asm volatile("s_waitcnt lgkmcnt(0)" ::: "memory"); __builtin_amdgcn_s_barrier(); asm volatile("" ::: "memory"); } while (0)
; #define RAWBAR() do { asm volatile("s_waitcnt lgkmcnt(0)" ::: "memory"); __builtin_amdgcn_s_barrier(); asm volatile("" ::: "memory"); } while (0)
; #define RAWBAR() do { asm volatile("s_waitcnt lgkmcnt(0)" ::: "memory"); __builtin_amdgcn_s_barrier(); asm volatile("" ::: "memory"); } while (0)
; #define RAWBAR() do { asm volatile("s_waitcnt lgkmcnt(0)" ::: "memory"); __builtin_amdgcn_s_barrier(); asm volatile("" ::: "memory"); } while (0)
; #define RAWBAR() do { asm volatile("s_waitcnt lgkmcnt(0)" ::: "memory"); __builtin_amdgcn_s_barrier(); asm volatile("" ::: "memory"); } while (0)
; template <int MODE> ...
;     ...
;   for (int j = 0; j < NT; ++j) {
;     const int buf = j & 1;
;     if (j + 1 < NT) { STAGE((j + 1) * KVBLK, buf ^ 1); }
;     const char* Kb = K_lds + buf * 16384;
;     f32x16 pe = {}, po = {};
; #pragma unroll
;     for (int d0 = 0; d0 < 8; d0 += 2) {
;       const bf16x8 k0 = *reinterpret_cast<const bf16x8*>(Kb + KSWZ(krow, (d0 * 16 + hi * 8) * 2));
;       const bf16x8 k1 = *reinterpret_cast<const bf16x8*>(Kb + KSWZ(krow, ((d0 + 1) * 16 + hi * 8) * 2));
;       pe = __builtin_amdgcn_mfma_f32_32x32x16_bf16(k0, qr[d0], pe, 0, 0, 0);
;       po = __builtin_amdgcn_mfma_f32_32x32x16_bf16(k1, qr[d0 + 1], po, 0, 0, 0); }
;     const int vo = vb0 + buf * 32768;
;     s16x4 R0_[8], R1_[8];
;     PVR(R0_, 0, 1, vo);
;     f32x16 p;
; #pragma unroll
;     for (int r = 0; r < 16; ++r) p[r] = __builtin_amdgcn_exp2f(fmaf(pe[r] + po[r], C, negMc));
;     float ps = 0.f;
; #pragma unroll
;     for (int r = 0; r < 16; ++r) ps += p[r];
;     lsum += ps;
;     const bf16x8 own0 = pk8(p, 0), own1 = pk8(p, 8);
;     SBAR();
;     PV_TAIL4(o, vo, vo + 16384, own0, own1);
;     asm volatile("s_waitcnt vmcnt(0)" ::: "memory");
;     RAWBAR();
;   }
.LattnB_m1:
	ds_read_b128 v[230:233], v229 offset:16384
	ds_read_b128 v[234:237], v228 offset:16384
	ds_read_b128 v[238:241], v227 offset:16384
	ds_read_b128 v[242:245], v226 offset:16384
	v_exp_f32_e32 v144, v144
	v_exp_f32_e32 v145, v145
	v_exp_f32_e32 v146, v146
	v_exp_f32_e32 v147, v147
	s_waitcnt lgkmcnt(2)
	v_mfma_f32_32x32x16_bf16 v[128:143], v[230:233], v[188:191], 0
	v_mfma_f32_32x32x16_bf16 v[128:143], v[234:237], v[184:187], v[128:143]
	ds_read_b128 v[230:233], v204 offset:16384
	ds_read_b128 v[234:237], v205 offset:16384
	v_exp_f32_e32 v148, v148
	v_exp_f32_e32 v149, v149
	v_exp_f32_e32 v150, v150
	v_exp_f32_e32 v151, v151
	v_add_f32_e32 v250, v144, v145
	v_add_f32_e32 v250, v146, v250
	v_add_f32_e32 v250, v147, v250
	s_waitcnt lgkmcnt(2)
	v_mfma_f32_32x32x16_bf16 v[128:143], v[238:241], v[180:183], v[128:143]
	v_mfma_f32_32x32x16_bf16 v[128:143], v[242:245], v[176:179], v[128:143]
	ds_read_b128 v[238:241], v206 offset:16384
	ds_read_b128 v[242:245], v207 offset:16384
	v_exp_f32_e32 v152, v152
	v_exp_f32_e32 v153, v153
	v_exp_f32_e32 v154, v154
	v_exp_f32_e32 v155, v155
	v_add_f32_e32 v250, v148, v250
	v_add_f32_e32 v250, v149, v250
	v_add_f32_e32 v250, v150, v250
	v_add_f32_e32 v250, v151, v250
	s_waitcnt lgkmcnt(2)
	v_mfma_f32_32x32x16_bf16 v[128:143], v[230:233], v[172:175], v[128:143]
	v_mfma_f32_32x32x16_bf16 v[128:143], v[234:237], v[168:171], v[128:143]
	v_exp_f32_e32 v156, v156
	v_exp_f32_e32 v157, v157
	v_exp_f32_e32 v158, v158
	v_exp_f32_e32 v159, v159
	v_add_f32_e32 v250, v152, v250
	v_add_f32_e32 v250, v153, v250
	v_add_f32_e32 v250, v154, v250
	v_add_f32_e32 v250, v155, v250
	v_cvt_pk_bf16_f32 v230, v144, v145
	v_cvt_pk_bf16_f32 v231, v146, v147
	v_cvt_pk_bf16_f32 v232, v148, v149
	v_cvt_pk_bf16_f32 v233, v150, v151
	s_waitcnt lgkmcnt(0)
	v_mfma_f32_32x32x16_bf16 v[128:143], v[238:241], v[164:167], v[128:143]
	v_mfma_f32_32x32x16_bf16 v[128:143], v[242:245], v[160:163], v[128:143]
	s_waitcnt vmcnt(0)
	s_barrier
	s_add_u32 s86, s86, 0x4000
	s_addc_u32 s87, s87, 0
	s_add_u32 s2, s2, 0x8000
	s_addc_u32 s3, s3, 0
	v_add_u32_e32 v249, s84, v218
	s_sub_u32 s85, s84, 0x8000
	s_cmp_eq_u32 s84, 0
	s_cselect_b32 s85, 0x10000, s85
	ds_read_b64_tr_b16 v[238:239], v249 offset:0
	ds_read_b64_tr_b16 v[240:241], v249 offset:2048
	ds_read_b64_tr_b16 v[242:243], v249 offset:512
	ds_read_b64_tr_b16 v[244:245], v249 offset:2560
	ds_read_b64_tr_b16 v[144:145], v249 offset:4096
	ds_read_b64_tr_b16 v[146:147], v249 offset:6144
	ds_read_b64_tr_b16 v[148:149], v249 offset:4608
	ds_read_b64_tr_b16 v[150:151], v249 offset:6656
	v_add_f32_e32 v250, v156, v250
	v_add_f32_e32 v250, v157, v250
	v_add_f32_e32 v250, v158, v250
	v_add_f32_e32 v250, v159, v250
	v_cvt_pk_bf16_f32 v234, v152, v153
	v_cvt_pk_bf16_f32 v235, v154, v155
	v_cvt_pk_bf16_f32 v236, v156, v157
	v_cvt_pk_bf16_f32 v237, v158, v159
	v_add_f32_e32 v219, v219, v250
	ds_read_b64_tr_b16 v[152:153], v249 offset:1024
	ds_read_b64_tr_b16 v[154:155], v249 offset:3072
	ds_read_b64_tr_b16 v[156:157], v249 offset:1536
	ds_read_b64_tr_b16 v[158:159], v249 offset:3584
	s_waitcnt lgkmcnt(8)
	v_mfma_f32_32x32x16_bf16 v[112:127], v[230:233], v[238:241], v[112:127]
	v_mfma_f32_32x32x16_bf16 v[96:111], v[230:233], v[242:245], v[96:111]
	s_add_i32 s30, s85, s34
	s_add_i32 m0, s30, 0x8000
	ds_read_b64_tr_b16 v[238:239], v249 offset:5120
	ds_read_b64_tr_b16 v[240:241], v249 offset:7168
	ds_read_b64_tr_b16 v[242:243], v249 offset:5632
	ds_read_b64_tr_b16 v[244:245], v249 offset:7680
	global_load_lds_dwordx4 v222, s[2:3] sc1
	s_waitcnt lgkmcnt(8)
	v_mfma_f32_32x32x16_bf16 v[112:127], v[234:237], v[144:147], v[112:127]
	v_mfma_f32_32x32x16_bf16 v[96:111], v[234:237], v[148:151], v[96:111]
	s_add_i32 s30, s85, s34
	s_add_i32 m0, s30, 0xa000
	ds_read_b64_tr_b16 v[144:145], v249 offset:16384
	ds_read_b64_tr_b16 v[146:147], v249 offset:18432
	ds_read_b64_tr_b16 v[148:149], v249 offset:16896
	ds_read_b64_tr_b16 v[150:151], v249 offset:18944
	global_load_lds_dwordx4 v221, s[2:3] sc1
	s_waitcnt lgkmcnt(8)
	v_mfma_f32_32x32x16_bf16 v[80:95], v[230:233], v[152:155], v[80:95]
	v_mfma_f32_32x32x16_bf16 v[64:79], v[230:233], v[156:159], v[64:79]
	s_add_i32 s30, s85, s34
	s_add_i32 m0, s30, 0xc000
	ds_read_b64_tr_b16 v[152:153], v249 offset:20480
	ds_read_b64_tr_b16 v[154:155], v249 offset:22528
	ds_read_b64_tr_b16 v[156:157], v249 offset:20992
	ds_read_b64_tr_b16 v[158:159], v249 offset:23040
	global_load_lds_dwordx4 v246, s[2:3] sc1
	s_waitcnt lgkmcnt(8)
	v_mfma_f32_32x32x16_bf16 v[80:95], v[234:237], v[238:241], v[80:95]
	v_mfma_f32_32x32x16_bf16 v[64:79], v[234:237], v[242:245], v[64:79]
	s_add_i32 s30, s85, s34
	s_add_i32 m0, s30, 0xe000
	ds_read_b64_tr_b16 v[238:239], v249 offset:17408
	ds_read_b64_tr_b16 v[240:241], v249 offset:19456
	ds_read_b64_tr_b16 v[242:243], v249 offset:17920
	ds_read_b64_tr_b16 v[244:245], v249 offset:19968
	global_load_lds_dwordx4 v247, s[2:3] sc1
	s_waitcnt lgkmcnt(8)
	v_mfma_f32_32x32x16_bf16 v[32:47], v[230:233], v[144:147], v[32:47]
	v_mfma_f32_32x32x16_bf16 v[16:31], v[230:233], v[148:151], v[16:31]
	s_add_i32 m0, s34, 0x4000
	ds_read_b64_tr_b16 v[144:145], v249 offset:21504
	ds_read_b64_tr_b16 v[146:147], v249 offset:23552
	ds_read_b64_tr_b16 v[148:149], v249 offset:22016
	ds_read_b64_tr_b16 v[150:151], v249 offset:24064
	global_load_lds_dwordx4 v225, s[86:87] sc1
	s_waitcnt lgkmcnt(8)
	v_mfma_f32_32x32x16_bf16 v[32:47], v[234:237], v[152:155], v[32:47]
	v_mfma_f32_32x32x16_bf16 v[16:31], v[234:237], v[156:159], v[16:31]
	s_add_i32 m0, s34, 0x6000
	s_nop 0
	global_load_lds_dwordx4 v223, s[86:87] sc1
	s_waitcnt lgkmcnt(0)
; #define SBAR() __builtin_amdgcn_sched_barrier(0)
; #define PVR(S, DA, DB, vbase) do { S[0] = tr_read<v_rd_off(DA, 0, 0)>(vbase); S[1] = tr_read<v_rd_off(DA, 0, 1)>(vbase); S[2] = tr_read<v_rd_off(DB, 0, 0)>(vbase); S[3] = tr_read<v_rd_off(DB, 0, 1)>(vbase); \
;     S[4] = tr_read<v_rd_off(DA, 1, 0)>(vbase); S[5] = tr_read<v_rd_off(DA, 1, 1)>(vbase); S[6] = tr_read<v_rd_off(DB, 1, 0)>(vbase); S[7] = tr_read<v_rd_off(DB, 1, 1)>(vbase); } while (0)
; #define RAWBAR() do { asm volatile("s_waitcnt lgkmcnt(0)" ::: "memory"); __builtin_amdgcn_s_barrier(); asm volatile("" ::: "memory"); } while (0)
; #define RAWBAR() do { asm volatile("s_waitcnt lgkmcnt(0)" ::: "memory"); __builtin_amdgcn_s_barrier(); asm volatile("" ::: "memory"); } while (0)
; #define RAWBAR() do { asm volatile("s_waitcnt lgkmcnt(0)" ::: "memory"); __builtin_amdgcn_s_barrier(); asm volatile("" ::: "memory"); } while (0)
; #define RAWBAR() do { asm volatile("s_waitcnt lgkmcnt(0)" ::: "memory"); __builtin_amdgcn_s_barrier(); asm volatile("" ::: "memory"); } while (0)
; #define RAWBAR() do { asm volatile("s_waitcnt lgkmcnt(0)" ::: "memory"); __builtin_amdgcn_s_barrier(); asm volatile("" ::: "memory"); } while (0)
; template <int MODE> ...
;     ...
;   for (int j = 0; j < NT; ++j) {
;     const int buf = j & 1;
;     if (j + 1 < NT) { STAGE((j + 1) * KVBLK, buf ^ 1); }
;     const char* Kb = K_lds + buf * 16384;
;     f32x16 pe = {}, po = {};
; #pragma unroll
;     for (int d0 = 0; d0 < 8; d0 += 2) {
;       const bf16x8 k0 = *reinterpret_cast<const bf16x8*>(Kb + KSWZ(krow, (d0 * 16 + hi * 8) * 2));
;       const bf16x8 k1 = *reinterpret_cast<const bf16x8*>(Kb + KSWZ(krow, ((d0 + 1) * 16 + hi * 8) * 2));
;       pe = __builtin_amdgcn_mfma_f32_32x32x16_bf16(k0, qr[d0], pe, 0, 0, 0);
;       po = __builtin_amdgcn_mfma_f32_32x32x16_bf16(k1, qr[d0 + 1], po, 0, 0, 0); }
;     const int vo = vb0 + buf * 32768;
;     s16x4 R0_[8], R1_[8];
;     PVR(R0_, 0, 1, vo);
;     f32x16 p;
; #pragma unroll
;     for (int r = 0; r < 16; ++r) p[r] = __builtin_amdgcn_exp2f(fmaf(pe[r] + po[r], C, negMc));
;     float ps = 0.f;
; #pragma unroll
;     for (int r = 0; r < 16; ++r) ps += p[r];
;     lsum += ps;
;     const bf16x8 own0 = pk8(p, 0), own1 = pk8(p, 8);
;     SBAR();
;     PV_TAIL4(o, vo, vo + 16384, own0, own1);
;     asm volatile("s_waitcnt vmcnt(0)" ::: "memory");
;     RAWBAR();
;   }
	v_mfma_f32_32x32x16_bf16 v[48:63], v[230:233], v[238:241], v[48:63]
	v_mfma_f32_32x32x16_bf16 v[0:15], v[230:233], v[242:245], v[0:15]
	v_mfma_f32_32x32x16_bf16 v[48:63], v[234:237], v[144:147], v[48:63]
	s_add_i32 s84, s84, 0x8000
	s_cmp_eq_u32 s84, 0x18000
	s_cselect_b32 s84, 0, s84
	v_mfma_f32_32x32x16_bf16 v[0:15], v[234:237], v[148:151], v[0:15]
	ds_read_b128 v[230:233], v229 offset:0
	ds_read_b128 v[234:237], v228 offset:0
	ds_read_b128 v[238:241], v227 offset:0
	ds_read_b128 v[242:245], v226 offset:0
	v_exp_f32_e32 v128, v128
	v_exp_f32_e32 v129, v129
	v_exp_f32_e32 v130, v130
	v_exp_f32_e32 v131, v131
	s_waitcnt lgkmcnt(2)
	v_mfma_f32_32x32x16_bf16 v[144:159], v[230:233], v[188:191], 0
	v_mfma_f32_32x32x16_bf16 v[144:159], v[234:237], v[184:187], v[144:159]
	ds_read_b128 v[230:233], v204 offset:0
	ds_read_b128 v[234:237], v205 offset:0
	v_exp_f32_e32 v132, v132
	v_exp_f32_e32 v133, v133
	v_exp_f32_e32 v134, v134
	v_exp_f32_e32 v135, v135
	v_add_f32_e32 v250, v128, v129
	v_add_f32_e32 v250, v130, v250
	v_add_f32_e32 v250, v131, v250
	s_waitcnt lgkmcnt(2)
	v_mfma_f32_32x32x16_bf16 v[144:159], v[238:241], v[180:183], v[144:159]
	v_mfma_f32_32x32x16_bf16 v[144:159], v[242:245], v[176:179], v[144:159]
	ds_read_b128 v[238:241], v206 offset:0
	ds_read_b128 v[242:245], v207 offset:0
	v_exp_f32_e32 v136, v136
	v_exp_f32_e32 v137, v137
	v_exp_f32_e32 v138, v138
	v_exp_f32_e32 v139, v139
	v_add_f32_e32 v250, v132, v250
	v_add_f32_e32 v250, v133, v250
	v_add_f32_e32 v250, v134, v250
	v_add_f32_e32 v250, v135, v250
	s_waitcnt lgkmcnt(2)
	v_mfma_f32_32x32x16_bf16 v[144:159], v[230:233], v[172:175], v[144:159]
	v_mfma_f32_32x32x16_bf16 v[144:159], v[234:237], v[168:171], v[144:159]
	v_exp_f32_e32 v140, v140
	v_exp_f32_e32 v141, v141
	v_exp_f32_e32 v142, v142
	v_exp_f32_e32 v143, v143
	v_add_f32_e32 v250, v136, v250
	v_add_f32_e32 v250, v137, v250
	v_add_f32_e32 v250, v138, v250
	v_add_f32_e32 v250, v139, v250
	v_cvt_pk_bf16_f32 v230, v128, v129
	v_cvt_pk_bf16_f32 v231, v130, v131
	v_cvt_pk_bf16_f32 v232, v132, v133
	v_cvt_pk_bf16_f32 v233, v134, v135
	s_waitcnt lgkmcnt(0)
	v_mfma_f32_32x32x16_bf16 v[144:159], v[238:241], v[164:167], v[144:159]
	v_mfma_f32_32x32x16_bf16 v[144:159], v[242:245], v[160:163], v[144:159]
	s_waitcnt vmcnt(0)
	s_barrier
	s_add_u32 s86, s86, 0x4000
	s_addc_u32 s87, s87, 0
	s_add_u32 s2, s2, 0x8000
	s_addc_u32 s3, s3, 0
	v_add_u32_e32 v249, s84, v218
	s_sub_u32 s85, s84, 0x8000
	s_cmp_eq_u32 s84, 0
	s_cselect_b32 s85, 0x10000, s85
	ds_read_b64_tr_b16 v[238:239], v249 offset:0
	ds_read_b64_tr_b16 v[240:241], v249 offset:2048
	ds_read_b64_tr_b16 v[242:243], v249 offset:512
	ds_read_b64_tr_b16 v[244:245], v249 offset:2560
	ds_read_b64_tr_b16 v[128:129], v249 offset:4096
	ds_read_b64_tr_b16 v[130:131], v249 offset:6144
	ds_read_b64_tr_b16 v[132:133], v249 offset:4608
	ds_read_b64_tr_b16 v[134:135], v249 offset:6656
	v_add_f32_e32 v250, v140, v250
	v_add_f32_e32 v250, v141, v250
	v_add_f32_e32 v250, v142, v250
	v_add_f32_e32 v250, v143, v250
	v_cvt_pk_bf16_f32 v234, v136, v137
	v_cvt_pk_bf16_f32 v235, v138, v139
	v_cvt_pk_bf16_f32 v236, v140, v141
	v_cvt_pk_bf16_f32 v237, v142, v143
	v_add_f32_e32 v219, v219, v250
	ds_read_b64_tr_b16 v[136:137], v249 offset:1024
	ds_read_b64_tr_b16 v[138:139], v249 offset:3072
	ds_read_b64_tr_b16 v[140:141], v249 offset:1536
	ds_read_b64_tr_b16 v[142:143], v249 offset:3584
	s_waitcnt lgkmcnt(8)
	v_mfma_f32_32x32x16_bf16 v[112:127], v[230:233], v[238:241], v[112:127]
	v_mfma_f32_32x32x16_bf16 v[96:111], v[230:233], v[242:245], v[96:111]
	s_add_i32 s30, s85, s34
	s_add_i32 m0, s30, 0x8000
	ds_read_b64_tr_b16 v[238:239], v249 offset:5120
	ds_read_b64_tr_b16 v[240:241], v249 offset:7168
	ds_read_b64_tr_b16 v[242:243], v249 offset:5632
	ds_read_b64_tr_b16 v[244:245], v249 offset:7680
	global_load_lds_dwordx4 v222, s[2:3] sc1
	s_waitcnt lgkmcnt(8)
	v_mfma_f32_32x32x16_bf16 v[112:127], v[234:237], v[128:131], v[112:127]
	v_mfma_f32_32x32x16_bf16 v[96:111], v[234:237], v[132:135], v[96:111]
	s_add_i32 s30, s85, s34
	s_add_i32 m0, s30, 0xa000
	ds_read_b64_tr_b16 v[128:129], v249 offset:16384
	ds_read_b64_tr_b16 v[130:131], v249 offset:18432
	ds_read_b64_tr_b16 v[132:133], v249 offset:16896
	ds_read_b64_tr_b16 v[134:135], v249 offset:18944
	global_load_lds_dwordx4 v221, s[2:3] sc1
	s_waitcnt lgkmcnt(8)
	v_mfma_f32_32x32x16_bf16 v[80:95], v[230:233], v[136:139], v[80:95]
	v_mfma_f32_32x32x16_bf16 v[64:79], v[230:233], v[140:143], v[64:79]
	s_add_i32 s30, s85, s34
	s_add_i32 m0, s30, 0xc000
	ds_read_b64_tr_b16 v[136:137], v249 offset:20480
	ds_read_b64_tr_b16 v[138:139], v249 offset:22528
	ds_read_b64_tr_b16 v[140:141], v249 offset:20992
	ds_read_b64_tr_b16 v[142:143], v249 offset:23040
	global_load_lds_dwordx4 v246, s[2:3] sc1
	s_waitcnt lgkmcnt(8)
	v_mfma_f32_32x32x16_bf16 v[80:95], v[234:237], v[238:241], v[80:95]
	v_mfma_f32_32x32x16_bf16 v[64:79], v[234:237], v[242:245], v[64:79]
	s_add_i32 s30, s85, s34
	s_add_i32 m0, s30, 0xe000
	ds_read_b64_tr_b16 v[238:239], v249 offset:17408
	ds_read_b64_tr_b16 v[240:241], v249 offset:19456
	ds_read_b64_tr_b16 v[242:243], v249 offset:17920
	ds_read_b64_tr_b16 v[244:245], v249 offset:19968
	global_load_lds_dwordx4 v247, s[2:3] sc1
	s_waitcnt lgkmcnt(8)
	v_mfma_f32_32x32x16_bf16 v[32:47], v[230:233], v[128:131], v[32:47]
	v_mfma_f32_32x32x16_bf16 v[16:31], v[230:233], v[132:135], v[16:31]
	s_mov_b32 m0, s34
	ds_read_b64_tr_b16 v[128:129], v249 offset:21504
	ds_read_b64_tr_b16 v[130:131], v249 offset:23552
	ds_read_b64_tr_b16 v[132:133], v249 offset:22016
	ds_read_b64_tr_b16 v[134:135], v249 offset:24064
	global_load_lds_dwordx4 v225, s[86:87] sc1
	s_waitcnt lgkmcnt(8)
	v_mfma_f32_32x32x16_bf16 v[32:47], v[234:237], v[136:139], v[32:47]
	v_mfma_f32_32x32x16_bf16 v[16:31], v[234:237], v[140:143], v[16:31]
	s_add_i32 m0, s34, 0x2000
	s_nop 0
	global_load_lds_dwordx4 v223, s[86:87] sc1
	s_waitcnt lgkmcnt(0)
	v_mfma_f32_32x32x16_bf16 v[48:63], v[230:233], v[238:241], v[48:63]
	v_mfma_f32_32x32x16_bf16 v[0:15], v[230:233], v[242:245], v[0:15]
	v_mfma_f32_32x32x16_bf16 v[48:63], v[234:237], v[128:131], v[48:63]
	s_add_i32 s84, s84, 0x8000
	s_cmp_eq_u32 s84, 0x18000
	s_cselect_b32 s84, 0, s84
	s_add_i32 s40, s40, 1
	s_cmpk_eq_i32 s40, 0x82
	v_mfma_f32_32x32x16_bf16 v[0:15], v[234:237], v[132:135], v[0:15]
	s_cbranch_scc0 .LattnB_m1
	s_waitcnt vmcnt(0)
	s_barrier
